# GEMM epilogues: cross-row (lane^16, lane^32) sum reductions via v_permlane16_swap/v_permlane32_swap instead of ds_bpermute round trips (same association)
# speedup vs baseline: 1.0247x; 1.0247x over previous
; __device__ __forceinline__ float shx(float v, int lane, int mask) { return __builtin_bit_cast(float, __builtin_amdgcn_ds_bpermute((lane ^ mask) << 2, __builtin_bit_cast(int, v))); }
;     __device__ __forceinline__ void operator()(AccT& acc, const Unit& u, int wr, int wc, int fr, int fq, PG8_LAS unsigned char* lds) const {
;     ...
;                 for (int m = 0; m < 4; ++m) { float s[2];
; #pragma unroll
;                     for (int bj = 0; bj < 2; ++bj) { const f32x4 a = acc[ai][bj][m][0], b = acc[ai][bj][m][1];
;                         s[bj] = ((a.x * a.x + a.y * a.y) + (a.z * a.z + a.w * a.w)) + ((b.x * b.x + b.y * b.y) + (b.z * b.z + b.w * b.w)); }
;                     if (NSEG == 1) { s[0] += s[1]; s[1] = 0.f; }
; #pragma unroll
;                     for (int sg = 0; sg < NSEG; ++sg) { float t = s[sg]; t += shx(t, fr + 16 * fq, 16); t += shx(t, fr + 16 * fq, 32);
;                         if (fq == 0) P[((ai * HALF + wr * 64 + m * 16 + fr) * 2 + sg) * 4 + wc] = t; } }
.LBB0_401:
	v_mul_f32_e32 v168, v125, v125
	v_mul_f32_e32 v169, v127, v127
	v_fmac_f32_e32 v168, v124, v124
	v_fmac_f32_e32 v169, v126, v126
	v_add_f32_e32 v168, v168, v169
	v_mul_f32_e32 v169, v121, v121
	v_mul_f32_e32 v182, v123, v123
	v_fmac_f32_e32 v169, v120, v120
	v_fmac_f32_e32 v182, v122, v122
	v_add_f32_e32 v169, v169, v182
	v_add_f32_e32 v168, v168, v169
	v_mul_f32_e32 v169, v117, v117
	v_mul_f32_e32 v182, v119, v119
	v_fmac_f32_e32 v169, v116, v116
	v_fmac_f32_e32 v182, v118, v118
	v_add_f32_e32 v169, v169, v182
	v_mul_f32_e32 v182, v113, v113
	v_mul_f32_e32 v183, v115, v115
	v_fmac_f32_e32 v182, v112, v112
	v_fmac_f32_e32 v183, v114, v114
	v_add_f32_e32 v182, v182, v183
	v_add_f32_e32 v169, v169, v182
	v_add_f32_e32 v168, v168, v169
	v_mov_b32_e32 v169, v168
	s_nop 1
	v_permlane16_swap_b32_e32 v168, v169
	s_waitcnt lgkmcnt(0)
	v_add_f32_e32 v169, v168, v169
	v_mov_b32_e32 v182, v169
	s_nop 1
	v_permlane32_swap_b32_e32 v169, v182
	v_add_u32_e32 v168, s64, v177
	s_and_saveexec_b64 s[0:1], s[40:41]
	s_cbranch_execz .LBB0_403
	s_waitcnt lgkmcnt(0)
	v_add_f32_e32 v169, v169, v182
	ds_write_b32 v168, v169
.LBB0_403:
	s_or_b64 exec, exec, s[0:1]
	v_mul_f32_e32 v169, v109, v109
	s_waitcnt lgkmcnt(0)
	v_mul_f32_e32 v182, v111, v111
	v_fmac_f32_e32 v169, v108, v108
	v_fmac_f32_e32 v182, v110, v110
	v_add_f32_e32 v169, v169, v182
	v_mul_f32_e32 v182, v105, v105
	v_mul_f32_e32 v183, v107, v107
	v_fmac_f32_e32 v182, v104, v104
	v_fmac_f32_e32 v183, v106, v106
	v_add_f32_e32 v182, v182, v183
	v_add_f32_e32 v169, v169, v182
	v_mul_f32_e32 v182, v101, v101
	v_mul_f32_e32 v183, v103, v103
	v_fmac_f32_e32 v182, v100, v100
	v_fmac_f32_e32 v183, v102, v102
	v_add_f32_e32 v182, v182, v183
	v_mul_f32_e32 v183, v97, v97
	v_mul_f32_e32 v184, v99, v99
	v_fmac_f32_e32 v183, v96, v96
	v_fmac_f32_e32 v184, v98, v98
	v_add_f32_e32 v183, v183, v184
	v_add_f32_e32 v182, v182, v183
	v_add_f32_e32 v169, v169, v182
	v_mov_b32_e32 v182, v169
	s_nop 1
	v_permlane16_swap_b32_e32 v169, v182
	s_waitcnt lgkmcnt(0)
	v_add_f32_e32 v169, v169, v182
	v_mov_b32_e32 v182, v169
	s_nop 1
	v_permlane32_swap_b32_e32 v169, v182
	s_and_saveexec_b64 s[0:1], s[40:41]
	s_cbranch_execz .LBB0_405
	s_waitcnt lgkmcnt(0)
	v_add_f32_e32 v169, v169, v182
	ds_write_b32 v168, v169 offset:512
.LBB0_405:
	s_or_b64 exec, exec, s[0:1]
	v_mul_f32_e32 v169, v93, v93
	s_waitcnt lgkmcnt(0)
	v_mul_f32_e32 v182, v95, v95
	v_fmac_f32_e32 v169, v92, v92
	v_fmac_f32_e32 v182, v94, v94
	v_add_f32_e32 v169, v169, v182
	v_mul_f32_e32 v182, v89, v89
	v_mul_f32_e32 v183, v91, v91
	v_fmac_f32_e32 v182, v88, v88
	v_fmac_f32_e32 v183, v90, v90
	v_add_f32_e32 v182, v182, v183
	v_add_f32_e32 v169, v169, v182
	v_mul_f32_e32 v182, v85, v85
	v_mul_f32_e32 v183, v87, v87
	v_fmac_f32_e32 v182, v84, v84
	v_fmac_f32_e32 v183, v86, v86
	v_add_f32_e32 v182, v182, v183
	v_mul_f32_e32 v183, v81, v81
	v_mul_f32_e32 v184, v83, v83
	v_fmac_f32_e32 v183, v80, v80
	v_fmac_f32_e32 v184, v82, v82
	v_add_f32_e32 v183, v183, v184
	v_add_f32_e32 v182, v182, v183
	v_add_f32_e32 v169, v169, v182
	v_mov_b32_e32 v182, v169
	s_nop 1
	v_permlane16_swap_b32_e32 v169, v182
	s_waitcnt lgkmcnt(0)
	v_add_f32_e32 v169, v169, v182
	v_mov_b32_e32 v182, v169
	s_nop 1
	v_permlane32_swap_b32_e32 v169, v182
	s_and_saveexec_b64 s[0:1], s[40:41]
	s_cbranch_execz .LBB0_407
	s_waitcnt lgkmcnt(0)
	v_add_f32_e32 v169, v169, v182
	ds_write_b32 v168, v169 offset:1024
.LBB0_407:
	s_or_b64 exec, exec, s[0:1]
	v_mul_f32_e32 v169, v77, v77
	s_waitcnt lgkmcnt(0)
	v_mul_f32_e32 v182, v79, v79
	v_fmac_f32_e32 v169, v76, v76
	v_fmac_f32_e32 v182, v78, v78
	v_add_f32_e32 v169, v169, v182
	v_mul_f32_e32 v182, v73, v73
	v_mul_f32_e32 v183, v75, v75
	v_fmac_f32_e32 v182, v72, v72
	v_fmac_f32_e32 v183, v74, v74
	v_add_f32_e32 v182, v182, v183
	v_add_f32_e32 v169, v169, v182
	v_mul_f32_e32 v182, v69, v69
	v_mul_f32_e32 v183, v71, v71
	v_fmac_f32_e32 v182, v68, v68
	v_fmac_f32_e32 v183, v70, v70
	v_add_f32_e32 v182, v182, v183
	v_mul_f32_e32 v183, v65, v65
	v_mul_f32_e32 v184, v67, v67
	v_fmac_f32_e32 v183, v64, v64
	v_fmac_f32_e32 v184, v66, v66
	v_add_f32_e32 v183, v183, v184
	v_add_f32_e32 v182, v182, v183
	v_add_f32_e32 v169, v169, v182
	v_mov_b32_e32 v182, v169
	s_nop 1
	v_permlane16_swap_b32_e32 v169, v182
	s_waitcnt lgkmcnt(0)
	v_add_f32_e32 v169, v169, v182
	v_mov_b32_e32 v182, v169
	s_nop 1
	v_permlane32_swap_b32_e32 v169, v182
	s_and_saveexec_b64 s[0:1], s[40:41]
	s_cbranch_execz .LBB0_409
	s_waitcnt lgkmcnt(0)
	v_add_f32_e32 v169, v169, v182
	ds_write_b32 v168, v169 offset:1536
; __device__ __forceinline__ float shx(float v, int lane, int mask) { return __builtin_bit_cast(float, __builtin_amdgcn_ds_bpermute((lane ^ mask) << 2, __builtin_bit_cast(int, v))); }
;     __device__ __forceinline__ void operator()(AccT& acc, const Unit& u, int wr, int wc, int fr, int fq, PG8_LAS unsigned char* lds) const {
;     ...
;                 for (int m = 0; m < 4; ++m) { float s[2];
; #pragma unroll
;                     for (int bj = 0; bj < 2; ++bj) { const f32x4 a = acc[ai][bj][m][0], b = acc[ai][bj][m][1];
;                         s[bj] = ((a.x * a.x + a.y * a.y) + (a.z * a.z + a.w * a.w)) + ((b.x * b.x + b.y * b.y) + (b.z * b.z + b.w * b.w)); }
;                     if (NSEG == 1) { s[0] += s[1]; s[1] = 0.f; }
; #pragma unroll
;                     for (int sg = 0; sg < NSEG; ++sg) { float t = s[sg]; t += shx(t, fr + 16 * fq, 16); t += shx(t, fr + 16 * fq, 32);
;                         if (fq == 0) P[((ai * HALF + wr * 64 + m * 16 + fr) * 2 + sg) * 4 + wc] = t; } }
.LBB0_409:
	s_or_b64 exec, exec, s[0:1]
	v_mul_f32_e32 v169, v61, v61
	s_waitcnt lgkmcnt(0)
	v_mul_f32_e32 v182, v63, v63
	v_fmac_f32_e32 v169, v60, v60
	v_fmac_f32_e32 v182, v62, v62
	v_add_f32_e32 v169, v169, v182
	v_mul_f32_e32 v182, v57, v57
	v_mul_f32_e32 v183, v59, v59
	v_fmac_f32_e32 v182, v56, v56
	v_fmac_f32_e32 v183, v58, v58
	v_add_f32_e32 v182, v182, v183
	v_add_f32_e32 v169, v169, v182
	v_mul_f32_e32 v182, v53, v53
	v_mul_f32_e32 v183, v55, v55
	v_fmac_f32_e32 v182, v52, v52
	v_fmac_f32_e32 v183, v54, v54
	v_add_f32_e32 v182, v182, v183
	v_mul_f32_e32 v183, v49, v49
	v_mul_f32_e32 v184, v51, v51
	v_fmac_f32_e32 v183, v48, v48
	v_fmac_f32_e32 v184, v50, v50
	v_add_f32_e32 v183, v183, v184
	v_add_f32_e32 v182, v182, v183
	v_add_f32_e32 v169, v169, v182
	v_mov_b32_e32 v182, v169
	s_nop 1
	v_permlane16_swap_b32_e32 v169, v182
	s_waitcnt lgkmcnt(0)
	v_add_f32_e32 v169, v169, v182
	v_mov_b32_e32 v182, v169
	s_nop 1
	v_permlane32_swap_b32_e32 v169, v182
	s_and_saveexec_b64 s[0:1], s[40:41]
	s_cbranch_execz .LBB0_411
	s_waitcnt lgkmcnt(0)
	v_add_f32_e32 v169, v169, v182
	ds_write_b32 v168, v169 offset:4096
.LBB0_411:
	s_or_b64 exec, exec, s[0:1]
	v_mul_f32_e32 v169, v45, v45
	s_waitcnt lgkmcnt(0)
	v_mul_f32_e32 v182, v47, v47
	v_fmac_f32_e32 v169, v44, v44
	v_fmac_f32_e32 v182, v46, v46
	v_add_f32_e32 v169, v169, v182
	v_mul_f32_e32 v182, v41, v41
	v_mul_f32_e32 v183, v43, v43
	v_fmac_f32_e32 v182, v40, v40
	v_fmac_f32_e32 v183, v42, v42
	v_add_f32_e32 v182, v182, v183
	v_add_f32_e32 v169, v169, v182
	v_mul_f32_e32 v182, v37, v37
	v_mul_f32_e32 v183, v39, v39
	v_fmac_f32_e32 v182, v36, v36
	v_fmac_f32_e32 v183, v38, v38
	v_add_f32_e32 v182, v182, v183
	v_mul_f32_e32 v183, v33, v33
	v_mul_f32_e32 v184, v35, v35
	v_fmac_f32_e32 v183, v32, v32
	v_fmac_f32_e32 v184, v34, v34
	v_add_f32_e32 v183, v183, v184
	v_add_f32_e32 v182, v182, v183
	v_add_f32_e32 v169, v169, v182
	v_mov_b32_e32 v182, v169
	s_nop 1
	v_permlane16_swap_b32_e32 v169, v182
	s_waitcnt lgkmcnt(0)
	v_add_f32_e32 v169, v169, v182
	v_mov_b32_e32 v182, v169
	s_nop 1
	v_permlane32_swap_b32_e32 v169, v182
	s_and_saveexec_b64 s[0:1], s[40:41]
	s_cbranch_execz .LBB0_413
	s_waitcnt lgkmcnt(0)
	v_add_f32_e32 v169, v169, v182
	ds_write_b32 v168, v169 offset:4608
.LBB0_413:
	s_or_b64 exec, exec, s[0:1]
	v_mul_f32_e32 v169, v29, v29
	s_waitcnt lgkmcnt(0)
	v_mul_f32_e32 v182, v31, v31
	v_fmac_f32_e32 v169, v28, v28
	v_fmac_f32_e32 v182, v30, v30
	v_add_f32_e32 v169, v169, v182
	v_mul_f32_e32 v182, v25, v25
	v_mul_f32_e32 v183, v27, v27
	v_fmac_f32_e32 v182, v24, v24
	v_fmac_f32_e32 v183, v26, v26
	v_add_f32_e32 v182, v182, v183
	v_add_f32_e32 v169, v169, v182
	v_mul_f32_e32 v182, v21, v21
	v_mul_f32_e32 v183, v23, v23
	v_fmac_f32_e32 v182, v20, v20
	v_fmac_f32_e32 v183, v22, v22
	v_add_f32_e32 v182, v182, v183
	v_mul_f32_e32 v183, v17, v17
	v_mul_f32_e32 v184, v19, v19
	v_fmac_f32_e32 v183, v16, v16
	v_fmac_f32_e32 v184, v18, v18
	v_add_f32_e32 v183, v183, v184
	v_add_f32_e32 v182, v182, v183
	v_add_f32_e32 v169, v169, v182
	v_mov_b32_e32 v182, v169
	s_nop 1
	v_permlane16_swap_b32_e32 v169, v182
	s_waitcnt lgkmcnt(0)
	v_add_f32_e32 v169, v169, v182
	v_mov_b32_e32 v182, v169
	s_nop 1
	v_permlane32_swap_b32_e32 v169, v182
	s_and_saveexec_b64 s[0:1], s[40:41]
	s_cbranch_execz .LBB0_415
	s_waitcnt lgkmcnt(0)
	v_add_f32_e32 v169, v169, v182
	ds_write_b32 v168, v169 offset:5120
.LBB0_415:
	s_or_b64 exec, exec, s[0:1]
	v_mul_f32_e32 v169, v13, v13
	s_waitcnt lgkmcnt(0)
	v_mul_f32_e32 v182, v15, v15
	v_fmac_f32_e32 v169, v12, v12
	v_fmac_f32_e32 v182, v14, v14
	v_add_f32_e32 v169, v169, v182
	v_mul_f32_e32 v182, v9, v9
	v_mul_f32_e32 v183, v11, v11
	v_fmac_f32_e32 v182, v8, v8
	v_fmac_f32_e32 v183, v10, v10
	v_add_f32_e32 v182, v182, v183
	v_add_f32_e32 v169, v169, v182
	v_mul_f32_e32 v182, v5, v5
	v_mul_f32_e32 v183, v7, v7
	v_fmac_f32_e32 v182, v4, v4
	v_fmac_f32_e32 v183, v6, v6
	v_add_f32_e32 v182, v182, v183
	v_mul_f32_e32 v183, v1, v1
	v_mul_f32_e32 v184, v3, v3
	v_fmac_f32_e32 v183, v0, v0
	v_fmac_f32_e32 v184, v2, v2
	v_add_f32_e32 v183, v183, v184
	v_add_f32_e32 v182, v182, v183
	v_add_f32_e32 v169, v169, v182
	v_mov_b32_e32 v182, v169
	s_nop 1
	v_permlane16_swap_b32_e32 v169, v182
	s_waitcnt lgkmcnt(0)
	v_add_f32_e32 v169, v169, v182
	v_mov_b32_e32 v182, v169
	s_nop 1
	v_permlane32_swap_b32_e32 v169, v182
	s_and_saveexec_b64 s[0:1], s[40:41]
	s_cbranch_execz .LBB0_417
	s_waitcnt lgkmcnt(0)
	v_add_f32_e32 v169, v169, v182
	ds_write_b32 v168, v169 offset:5632

; __device__ __forceinline__ unsigned cvt_pk_bf16(float lo, float hi) { unsigned r; asm volatile("v_cvt_pk_bf16_f32 %0, %1, %2" : "=v"(r) : "v"(lo), "v"(hi)); return r; }
; __device__ __forceinline__ float shx(float v, int lane, int mask) { return __builtin_bit_cast(float, __builtin_amdgcn_ds_bpermute((lane ^ mask) << 2, __builtin_bit_cast(int, v))); }
; __device__ __forceinline__ f32x4 bf_lo4(unsigned a, unsigned b) { return (f32x4){__uint_as_float(a << 16), __uint_as_float(a & 0xffff0000u), __uint_as_float(b << 16), __uint_as_float(b & 0xffff0000u)}; }
;     __device__ __forceinline__ void operator()(AccT& acc, const Unit& u, int wr, int wc, int fr, int fq, PG8_LAS unsigned char*) const {
;     ...
;             for (int m = 0; m < 4; ++m) bs[ai][m] = *(const u32x4*)(hb + (size_t)(u.pm * BM + ai * HALF + wr * 64 + m * 16 + fr) * 1024 + col0);
; #pragma unroll
;         for (int ai = 0; ai < 2; ++ai)
; #pragma unroll
;             for (int m = 0; m < 4; ++m) { const int row = u.pm * BM + ai * HALF + wr * 64 + m * 16 + fr; const size_t off = (size_t)row * 1024 + col0;
;                 const u32x4 bb = bs[ai][m];
;                 f32x4 v0 = bf_lo4(bb.x, bb.y), v1 = bf_lo4(bb.z, bb.w);
;                 const f32x4 a0 = acc[ai][0][m][0], a1 = acc[ai][0][m][1], g0 = acc[ai][1][m][0], g1 = acc[ai][1][m][1];
; #pragma unroll
;                 for (int j = 0; j < 4; ++j) { v0[j] += a0[j] * __builtin_amdgcn_rcpf(1.f + __builtin_amdgcn_exp2f(-1.4426950408889634f * g0[j]));
;                                               v1[j] += a1[j] * __builtin_amdgcn_rcpf(1.f + __builtin_amdgcn_exp2f(-1.4426950408889634f * g1[j])); }
;                 u32x4 w; w.x = cvt_pk_bf16(v0.x, v0.y); w.y = cvt_pk_bf16(v0.z, v0.w); w.z = cvt_pk_bf16(v1.x, v1.y); w.w = cvt_pk_bf16(v1.z, v1.w);
;                 *(u32x4*)(hb + off) = w;
;                 float ss = ((v0.x * v0.x + v0.y * v0.y) + (v0.z * v0.z + v0.w * v0.w)) + ((v1.x * v1.x + v1.y * v1.y) + (v1.z * v1.z + v1.w * v1.w));
;                 ss += shx(ss, lane, 16); ss += shx(ss, lane, 32);
;                 if (fq == 0) ssq[(size_t)row * 32 + u.pn * 4 + wc] = ss; }
.LBB0_456:
	v_lshl_or_b32 v170, s55, 7, v205
	v_lshl_add_u32 v200, s2, 8, v202
	v_ashrrev_i32_e32 v171, 31, v170
	v_lshlrev_b64 v[222:223], 1, v[170:171]
	v_ashrrev_i32_e32 v201, 31, v200
	v_lshl_add_u64 v[112:113], s[12:13], 0, v[222:223]
	v_lshlrev_b64 v[224:225], 11, v[200:201]
	v_lshl_add_u64 v[114:115], v[112:113], 0, v[224:225]
	global_load_dwordx4 v[218:221], v[114:115], off
	v_or_b32_e32 v196, 16, v200
	v_or_b32_e32 v192, 32, v200
	v_or_b32_e32 v188, 48, v200
	v_add_u32_e32 v184, 0x80, v200
	v_add_u32_e32 v180, 0x90, v200
	v_add_u32_e32 v176, 0xa0, v200
	v_add_u32_e32 v172, 0xb0, v200
	v_ashrrev_i32_e32 v197, 31, v196
	v_ashrrev_i32_e32 v193, 31, v192
	v_ashrrev_i32_e32 v189, 31, v188
	v_ashrrev_i32_e32 v185, 31, v184
	v_ashrrev_i32_e32 v181, 31, v180
	v_ashrrev_i32_e32 v177, 31, v176
	v_ashrrev_i32_e32 v173, 31, v172
	v_lshlrev_b64 v[198:199], 11, v[196:197]
	v_lshlrev_b64 v[194:195], 11, v[192:193]
	v_lshlrev_b64 v[190:191], 11, v[188:189]
	v_lshlrev_b64 v[186:187], 11, v[184:185]
	v_lshlrev_b64 v[182:183], 11, v[180:181]
	v_lshlrev_b64 v[178:179], 11, v[176:177]
	v_lshlrev_b64 v[174:175], 11, v[172:173]
	v_lshl_add_u64 v[114:115], v[112:113], 0, v[198:199]
	v_lshl_add_u64 v[132:133], v[112:113], 0, v[194:195]
	v_lshl_add_u64 v[134:135], v[112:113], 0, v[190:191]
	v_lshl_add_u64 v[136:137], v[112:113], 0, v[186:187]
	v_lshl_add_u64 v[138:139], v[112:113], 0, v[182:183]
	v_lshl_add_u64 v[238:239], v[112:113], 0, v[178:179]
	v_lshl_add_u64 v[112:113], v[112:113], 0, v[174:175]
	global_load_dwordx4 v[152:155], v[114:115], off
	global_load_dwordx4 v[148:151], v[132:133], off
	global_load_dwordx4 v[144:147], v[134:135], off
	global_load_dwordx4 v[140:143], v[136:137], off
	s_nop 0
	global_load_dwordx4 v[136:139], v[138:139], off
	s_nop 0
	global_load_dwordx4 v[132:135], v[238:239], off
	s_nop 0
	global_load_dwordx4 v[112:115], v[112:113], off
	v_mul_f32_e32 v124, 0xbfb8aa3b, v124
	v_exp_f32_e32 v124, v124
	v_mul_f32_e32 v129, 0xbfb8aa3b, v129
	v_mul_f32_e32 v131, 0xbfb8aa3b, v131
	v_mul_f32_e32 v128, 0xbfb8aa3b, v128
	v_mul_f32_e32 v125, 0xbfb8aa3b, v125
	v_mul_f32_e32 v130, 0xbfb8aa3b, v130
	v_mul_f32_e32 v127, 0xbfb8aa3b, v127
	v_exp_f32_e32 v129, v129
	v_exp_f32_e32 v131, v131
	v_add_f32_e32 v124, 1.0, v124
	v_exp_f32_e32 v128, v128
	v_exp_f32_e32 v125, v125
	v_exp_f32_e32 v130, v130
	v_exp_f32_e32 v127, v127
	v_rcp_f32_e32 v124, v124
	v_mul_f32_e32 v126, 0xbfb8aa3b, v126
	v_exp_f32_e32 v126, v126
	v_add_f32_e32 v129, 1.0, v129
	v_add_f32_e32 v131, 1.0, v131
	v_add_f32_e32 v128, 1.0, v128
	v_add_f32_e32 v125, 1.0, v125
	v_add_f32_e32 v130, 1.0, v130
	v_rcp_f32_e32 v129, v129
	v_rcp_f32_e32 v131, v131
	v_rcp_f32_e32 v128, v128
	v_rcp_f32_e32 v125, v125
	v_rcp_f32_e32 v130, v130
	v_add_f32_e32 v126, 1.0, v126
	v_rcp_f32_e32 v126, v126
	s_lshl_b32 s2, s55, 2
	s_ashr_i32 s3, s2, 31
	s_waitcnt vmcnt(0)
	v_lshlrev_b32_e32 v239, 16, v220
	v_fmac_f32_e32 v239, v116, v124
	v_add_f32_e32 v116, 1.0, v127
	v_rcp_f32_e32 v116, v116
	v_lshlrev_b32_e32 v237, 16, v218
	v_and_b32_e32 v218, 0xffff0000, v218
	v_lshlrev_b32_e32 v238, 16, v219
	v_and_b32_e32 v219, 0xffff0000, v219
	v_and_b32_e32 v220, 0xffff0000, v220
	v_lshlrev_b32_e32 v240, 16, v221
	v_and_b32_e32 v221, 0xffff0000, v221
	v_fmac_f32_e32 v218, v121, v129
	v_fmac_f32_e32 v219, v123, v131
	v_fmac_f32_e32 v237, v120, v128
	v_fmac_f32_e32 v220, v117, v125
	v_fmac_f32_e32 v238, v122, v130
	v_fmac_f32_e32 v221, v119, v116
	v_mul_f32_e32 v116, v218, v218
	v_mul_f32_e32 v117, v219, v219
	v_fmac_f32_e32 v116, v237, v237
	v_fmac_f32_e32 v117, v238, v238
	v_fmac_f32_e32 v240, v118, v126
	v_add_f32_e32 v116, v116, v117
	v_mul_f32_e32 v117, v220, v220
	v_mul_f32_e32 v118, v221, v221
	v_fmac_f32_e32 v117, v239, v239
	v_fmac_f32_e32 v118, v240, v240
	v_add_f32_e32 v117, v117, v118
	v_add_f32_e32 v116, v116, v117
	v_mov_b32_e32 v117, v116
	s_nop 1
	v_permlane16_swap_b32_e32 v116, v117
	v_lshl_add_u64 v[122:123], s[12:13], 0, v[224:225]
	v_lshl_add_u64 v[122:123], v[122:123], 0, v[222:223]
	v_cvt_pk_bf16_f32 v118, v237, v218
	v_cvt_pk_bf16_f32 v119, v238, v219
	s_waitcnt lgkmcnt(0)
	v_add_f32_e32 v116, v116, v117
	v_mov_b32_e32 v117, v116
	s_nop 1
	v_permlane32_swap_b32_e32 v116, v117
	v_cvt_pk_bf16_f32 v120, v239, v220
	v_cvt_pk_bf16_f32 v121, v240, v221
	global_store_dwordx4 v[122:123], v[118:121], off
	s_and_saveexec_b64 s[18:19], s[38:39]
	s_cbranch_execz .LBB0_458
	s_waitcnt lgkmcnt(0)
	v_add_f32_e32 v118, v116, v117
	v_lshlrev_b64 v[116:117], 7, v[200:201]
	v_lshl_add_u64 v[116:117], s[14:15], 0, v[116:117]
	v_lshl_add_u64 v[116:117], s[2:3], 2, v[116:117]
	s_lshl_b32 s96, s49, 2
	v_lshl_add_u64 v[116:117], v[116:117], 0, s[96:97]
	global_store_dword v[116:117], v118, off
; __device__ __forceinline__ unsigned cvt_pk_bf16(float lo, float hi) { unsigned r; asm volatile("v_cvt_pk_bf16_f32 %0, %1, %2" : "=v"(r) : "v"(lo), "v"(hi)); return r; }
; __device__ __forceinline__ float shx(float v, int lane, int mask) { return __builtin_bit_cast(float, __builtin_amdgcn_ds_bpermute((lane ^ mask) << 2, __builtin_bit_cast(int, v))); }
; __device__ __forceinline__ f32x4 bf_lo4(unsigned a, unsigned b) { return (f32x4){__uint_as_float(a << 16), __uint_as_float(a & 0xffff0000u), __uint_as_float(b << 16), __uint_as_float(b & 0xffff0000u)}; }
;     __device__ __forceinline__ void operator()(AccT& acc, const Unit& u, int wr, int wc, int fr, int fq, PG8_LAS unsigned char*) const {
;     ...
;             for (int m = 0; m < 4; ++m) { const int row = u.pm * BM + ai * HALF + wr * 64 + m * 16 + fr; const size_t off = (size_t)row * 1024 + col0;
;                 const u32x4 bb = bs[ai][m];
;                 f32x4 v0 = bf_lo4(bb.x, bb.y), v1 = bf_lo4(bb.z, bb.w);
;                 const f32x4 a0 = acc[ai][0][m][0], a1 = acc[ai][0][m][1], g0 = acc[ai][1][m][0], g1 = acc[ai][1][m][1];
; #pragma unroll
;                 for (int j = 0; j < 4; ++j) { v0[j] += a0[j] * __builtin_amdgcn_rcpf(1.f + __builtin_amdgcn_exp2f(-1.4426950408889634f * g0[j]));
;                                               v1[j] += a1[j] * __builtin_amdgcn_rcpf(1.f + __builtin_amdgcn_exp2f(-1.4426950408889634f * g1[j])); }
;                 u32x4 w; w.x = cvt_pk_bf16(v0.x, v0.y); w.y = cvt_pk_bf16(v0.z, v0.w); w.z = cvt_pk_bf16(v1.x, v1.y); w.w = cvt_pk_bf16(v1.z, v1.w);
;                 *(u32x4*)(hb + off) = w;
;                 float ss = ((v0.x * v0.x + v0.y * v0.y) + (v0.z * v0.z + v0.w * v0.w)) + ((v1.x * v1.x + v1.y * v1.y) + (v1.z * v1.z + v1.w * v1.w));
;                 ss += shx(ss, lane, 16); ss += shx(ss, lane, 32);
;                 if (fq == 0) ssq[(size_t)row * 32 + u.pn * 4 + wc] = ss; }
.LBB0_458:
	s_or_b64 exec, exec, s[18:19]
	v_mul_f32_e32 v96, 0xbfb8aa3b, v96
	v_exp_f32_e32 v96, v96
	v_mul_f32_e32 v97, 0xbfb8aa3b, v97
	v_exp_f32_e32 v97, v97
	v_lshlrev_b32_e32 v120, 16, v154
	v_add_f32_e32 v96, 1.0, v96
	v_rcp_f32_e32 v96, v96
	v_mul_f32_e32 v98, 0xbfb8aa3b, v98
	v_exp_f32_e32 v98, v98
	v_and_b32_e32 v121, 0xffff0000, v154
	v_fmac_f32_e32 v120, v104, v96
	v_add_f32_e32 v96, 1.0, v97
	v_mul_f32_e32 v97, 0xbfb8aa3b, v102
	v_rcp_f32_e32 v96, v96
	v_exp_f32_e32 v97, v97
	v_mul_f32_e32 v101, 0xbfb8aa3b, v101
	v_mul_f32_e32 v100, 0xbfb8aa3b, v100
	v_fmac_f32_e32 v121, v105, v96
	v_add_f32_e32 v96, 1.0, v97
	v_add_f32_e32 v97, 1.0, v98
	v_mul_f32_e32 v98, 0xbfb8aa3b, v103
	v_exp_f32_e32 v101, v101
	v_exp_f32_e32 v98, v98
	v_exp_f32_e32 v100, v100
	v_mul_f32_e32 v99, 0xbfb8aa3b, v99
	v_exp_f32_e32 v99, v99
	v_add_f32_e32 v101, 1.0, v101
	v_add_f32_e32 v98, 1.0, v98
	v_add_f32_e32 v100, 1.0, v100
	v_rcp_f32_e32 v101, v101
	v_rcp_f32_e32 v98, v98
	v_rcp_f32_e32 v100, v100
	v_rcp_f32_e32 v96, v96
	v_rcp_f32_e32 v97, v97
	v_add_f32_e32 v99, 1.0, v99
	v_rcp_f32_e32 v99, v99
	s_waitcnt lgkmcnt(0)
	v_and_b32_e32 v117, 0xffff0000, v152
	v_and_b32_e32 v119, 0xffff0000, v153
	v_lshlrev_b32_e32 v116, 16, v152
	v_lshlrev_b32_e32 v118, 16, v153
	v_lshlrev_b32_e32 v122, 16, v155
	v_fmac_f32_e32 v117, v109, v101
	v_fmac_f32_e32 v119, v111, v98
	v_and_b32_e32 v123, 0xffff0000, v155
	v_fmac_f32_e32 v116, v108, v100
	v_fmac_f32_e32 v118, v110, v96
	v_fmac_f32_e32 v122, v106, v97
	v_mul_f32_e32 v96, v117, v117
	v_mul_f32_e32 v97, v119, v119
	v_fmac_f32_e32 v123, v107, v99
	v_fmac_f32_e32 v96, v116, v116
	v_fmac_f32_e32 v97, v118, v118
	v_add_f32_e32 v96, v96, v97
	v_mul_f32_e32 v97, v121, v121
	v_mul_f32_e32 v98, v123, v123
	v_fmac_f32_e32 v97, v120, v120
	v_fmac_f32_e32 v98, v122, v122
	v_add_f32_e32 v97, v97, v98
	v_add_f32_e32 v96, v96, v97
	v_mov_b32_e32 v97, v96
	s_nop 1
	v_permlane16_swap_b32_e32 v96, v97
	v_lshl_add_u64 v[102:103], s[12:13], 0, v[198:199]
	v_lshl_add_u64 v[102:103], v[170:171], 1, v[102:103]
	v_cvt_pk_bf16_f32 v98, v116, v117
	v_cvt_pk_bf16_f32 v99, v118, v119
	s_waitcnt lgkmcnt(0)
	v_add_f32_e32 v96, v96, v97
	v_mov_b32_e32 v97, v96
	s_nop 1
	v_permlane32_swap_b32_e32 v96, v97
	v_cvt_pk_bf16_f32 v100, v120, v121
	v_cvt_pk_bf16_f32 v101, v122, v123
	global_store_dwordx4 v[102:103], v[98:101], off
	s_and_saveexec_b64 s[18:19], s[38:39]
	s_cbranch_execz .LBB0_460
	s_waitcnt lgkmcnt(0)
	v_add_f32_e32 v98, v96, v97
	v_lshlrev_b64 v[96:97], 7, v[196:197]
	v_lshl_add_u64 v[96:97], s[14:15], 0, v[96:97]
	v_lshl_add_u64 v[96:97], s[2:3], 2, v[96:97]
	s_lshl_b32 s96, s49, 2
	v_lshl_add_u64 v[96:97], v[96:97], 0, s[96:97]
	global_store_dword v[96:97], v98, off
.LBB0_460:
	s_or_b64 exec, exec, s[18:19]
	v_mul_f32_e32 v80, 0xbfb8aa3b, v80
	v_exp_f32_e32 v80, v80
	v_mul_f32_e32 v81, 0xbfb8aa3b, v81
	v_exp_f32_e32 v81, v81
	v_lshlrev_b32_e32 v100, 16, v150
	v_add_f32_e32 v80, 1.0, v80
	v_rcp_f32_e32 v80, v80
	v_mul_f32_e32 v82, 0xbfb8aa3b, v82
	v_exp_f32_e32 v82, v82
	v_and_b32_e32 v101, 0xffff0000, v150
	v_fmac_f32_e32 v100, v88, v80
	v_add_f32_e32 v80, 1.0, v81
	v_mul_f32_e32 v81, 0xbfb8aa3b, v86
	v_rcp_f32_e32 v80, v80
	v_exp_f32_e32 v81, v81
	v_mul_f32_e32 v85, 0xbfb8aa3b, v85
	v_mul_f32_e32 v84, 0xbfb8aa3b, v84
	v_fmac_f32_e32 v101, v89, v80
	v_add_f32_e32 v80, 1.0, v81
	v_add_f32_e32 v81, 1.0, v82
	v_mul_f32_e32 v82, 0xbfb8aa3b, v87
	v_exp_f32_e32 v85, v85
	v_exp_f32_e32 v82, v82
	v_exp_f32_e32 v84, v84
	v_mul_f32_e32 v83, 0xbfb8aa3b, v83
	v_exp_f32_e32 v83, v83
	v_add_f32_e32 v85, 1.0, v85
	v_add_f32_e32 v82, 1.0, v82
	v_add_f32_e32 v84, 1.0, v84
	v_rcp_f32_e32 v85, v85
	v_rcp_f32_e32 v82, v82
	v_rcp_f32_e32 v84, v84
	v_rcp_f32_e32 v80, v80
	v_rcp_f32_e32 v81, v81
	v_add_f32_e32 v83, 1.0, v83
	v_rcp_f32_e32 v83, v83
	s_waitcnt lgkmcnt(0)
	v_and_b32_e32 v97, 0xffff0000, v148
	v_and_b32_e32 v99, 0xffff0000, v149
	v_lshlrev_b32_e32 v96, 16, v148
	v_lshlrev_b32_e32 v98, 16, v149
	v_lshlrev_b32_e32 v102, 16, v151
	v_fmac_f32_e32 v97, v93, v85
	v_fmac_f32_e32 v99, v95, v82
	v_and_b32_e32 v103, 0xffff0000, v151
	v_fmac_f32_e32 v96, v92, v84
	v_fmac_f32_e32 v98, v94, v80
	v_fmac_f32_e32 v102, v90, v81
	v_mul_f32_e32 v80, v97, v97
	v_mul_f32_e32 v81, v99, v99
	v_fmac_f32_e32 v103, v91, v83
	v_fmac_f32_e32 v80, v96, v96
	v_fmac_f32_e32 v81, v98, v98
	v_add_f32_e32 v80, v80, v81
	v_mul_f32_e32 v81, v101, v101
	v_mul_f32_e32 v82, v103, v103
	v_fmac_f32_e32 v81, v100, v100
	v_fmac_f32_e32 v82, v102, v102
	v_add_f32_e32 v81, v81, v82
	v_add_f32_e32 v80, v80, v81
	v_mov_b32_e32 v81, v80
	s_nop 1
	v_permlane16_swap_b32_e32 v80, v81
	v_lshl_add_u64 v[86:87], s[12:13], 0, v[194:195]
	v_lshl_add_u64 v[86:87], v[170:171], 1, v[86:87]
	v_cvt_pk_bf16_f32 v82, v96, v97
	v_cvt_pk_bf16_f32 v83, v98, v99
	s_waitcnt lgkmcnt(0)
	v_add_f32_e32 v80, v80, v81
	v_mov_b32_e32 v81, v80
	s_nop 1
	v_permlane32_swap_b32_e32 v80, v81
	v_cvt_pk_bf16_f32 v84, v100, v101
	v_cvt_pk_bf16_f32 v85, v102, v103
	global_store_dwordx4 v[86:87], v[82:85], off
	s_and_saveexec_b64 s[18:19], s[38:39]
	s_cbranch_execz .LBB0_462
	s_waitcnt lgkmcnt(0)
	v_add_f32_e32 v82, v80, v81
	v_lshlrev_b64 v[80:81], 7, v[192:193]
	v_lshl_add_u64 v[80:81], s[14:15], 0, v[80:81]
	v_lshl_add_u64 v[80:81], s[2:3], 2, v[80:81]
	s_lshl_b32 s96, s49, 2
	v_lshl_add_u64 v[80:81], v[80:81], 0, s[96:97]
	global_store_dword v[80:81], v82, off
; __device__ __forceinline__ unsigned cvt_pk_bf16(float lo, float hi) { unsigned r; asm volatile("v_cvt_pk_bf16_f32 %0, %1, %2" : "=v"(r) : "v"(lo), "v"(hi)); return r; }
; __device__ __forceinline__ float shx(float v, int lane, int mask) { return __builtin_bit_cast(float, __builtin_amdgcn_ds_bpermute((lane ^ mask) << 2, __builtin_bit_cast(int, v))); }
; __device__ __forceinline__ f32x4 bf_lo4(unsigned a, unsigned b) { return (f32x4){__uint_as_float(a << 16), __uint_as_float(a & 0xffff0000u), __uint_as_float(b << 16), __uint_as_float(b & 0xffff0000u)}; }
;     __device__ __forceinline__ void operator()(AccT& acc, const Unit& u, int wr, int wc, int fr, int fq, PG8_LAS unsigned char*) const {
;     ...
;             for (int m = 0; m < 4; ++m) { const int row = u.pm * BM + ai * HALF + wr * 64 + m * 16 + fr; const size_t off = (size_t)row * 1024 + col0;
;                 const u32x4 bb = bs[ai][m];
;                 f32x4 v0 = bf_lo4(bb.x, bb.y), v1 = bf_lo4(bb.z, bb.w);
;                 const f32x4 a0 = acc[ai][0][m][0], a1 = acc[ai][0][m][1], g0 = acc[ai][1][m][0], g1 = acc[ai][1][m][1];
; #pragma unroll
;                 for (int j = 0; j < 4; ++j) { v0[j] += a0[j] * __builtin_amdgcn_rcpf(1.f + __builtin_amdgcn_exp2f(-1.4426950408889634f * g0[j]));
;                                               v1[j] += a1[j] * __builtin_amdgcn_rcpf(1.f + __builtin_amdgcn_exp2f(-1.4426950408889634f * g1[j])); }
;                 u32x4 w; w.x = cvt_pk_bf16(v0.x, v0.y); w.y = cvt_pk_bf16(v0.z, v0.w); w.z = cvt_pk_bf16(v1.x, v1.y); w.w = cvt_pk_bf16(v1.z, v1.w);
;                 *(u32x4*)(hb + off) = w;
;                 float ss = ((v0.x * v0.x + v0.y * v0.y) + (v0.z * v0.z + v0.w * v0.w)) + ((v1.x * v1.x + v1.y * v1.y) + (v1.z * v1.z + v1.w * v1.w));
;                 ss += shx(ss, lane, 16); ss += shx(ss, lane, 32);
;                 if (fq == 0) ssq[(size_t)row * 32 + u.pn * 4 + wc] = ss; }
.LBB0_462:
	s_or_b64 exec, exec, s[18:19]
	v_mul_f32_e32 v64, 0xbfb8aa3b, v64
	v_exp_f32_e32 v64, v64
	v_mul_f32_e32 v65, 0xbfb8aa3b, v65
	v_exp_f32_e32 v65, v65
	v_lshlrev_b32_e32 v84, 16, v146
	v_add_f32_e32 v64, 1.0, v64
	v_rcp_f32_e32 v64, v64
	v_mul_f32_e32 v66, 0xbfb8aa3b, v66
	v_exp_f32_e32 v66, v66
	v_and_b32_e32 v85, 0xffff0000, v146
	v_fmac_f32_e32 v84, v72, v64
	v_add_f32_e32 v64, 1.0, v65
	v_mul_f32_e32 v65, 0xbfb8aa3b, v70
	v_rcp_f32_e32 v64, v64
	v_exp_f32_e32 v65, v65
	v_mul_f32_e32 v69, 0xbfb8aa3b, v69
	v_mul_f32_e32 v68, 0xbfb8aa3b, v68
	v_fmac_f32_e32 v85, v73, v64
	v_add_f32_e32 v64, 1.0, v65
	v_add_f32_e32 v65, 1.0, v66
	v_mul_f32_e32 v66, 0xbfb8aa3b, v71
	v_exp_f32_e32 v69, v69
	v_exp_f32_e32 v66, v66
	v_exp_f32_e32 v68, v68
	v_mul_f32_e32 v67, 0xbfb8aa3b, v67
	v_exp_f32_e32 v67, v67
	v_add_f32_e32 v69, 1.0, v69
	v_add_f32_e32 v66, 1.0, v66
	v_add_f32_e32 v68, 1.0, v68
	v_rcp_f32_e32 v69, v69
	v_rcp_f32_e32 v66, v66
	v_rcp_f32_e32 v68, v68
	v_rcp_f32_e32 v64, v64
	v_rcp_f32_e32 v65, v65
	v_add_f32_e32 v67, 1.0, v67
	v_rcp_f32_e32 v67, v67
	s_waitcnt lgkmcnt(0)
	v_and_b32_e32 v81, 0xffff0000, v144
	v_and_b32_e32 v83, 0xffff0000, v145
	v_lshlrev_b32_e32 v80, 16, v144
	v_lshlrev_b32_e32 v82, 16, v145
	v_lshlrev_b32_e32 v86, 16, v147
	v_fmac_f32_e32 v81, v77, v69
	v_fmac_f32_e32 v83, v79, v66
	v_and_b32_e32 v87, 0xffff0000, v147
	v_fmac_f32_e32 v80, v76, v68
	v_fmac_f32_e32 v82, v78, v64
	v_fmac_f32_e32 v86, v74, v65
	v_mul_f32_e32 v64, v81, v81
	v_mul_f32_e32 v65, v83, v83
	v_fmac_f32_e32 v87, v75, v67
	v_fmac_f32_e32 v64, v80, v80
	v_fmac_f32_e32 v65, v82, v82
	v_add_f32_e32 v64, v64, v65
	v_mul_f32_e32 v65, v85, v85
	v_mul_f32_e32 v66, v87, v87
	v_fmac_f32_e32 v65, v84, v84
	v_fmac_f32_e32 v66, v86, v86
	v_add_f32_e32 v65, v65, v66
	v_add_f32_e32 v64, v64, v65
	v_mov_b32_e32 v65, v64
	s_nop 1
	v_permlane16_swap_b32_e32 v64, v65
	v_lshl_add_u64 v[70:71], s[12:13], 0, v[190:191]
	v_lshl_add_u64 v[70:71], v[170:171], 1, v[70:71]
	v_cvt_pk_bf16_f32 v66, v80, v81
	v_cvt_pk_bf16_f32 v67, v82, v83
	s_waitcnt lgkmcnt(0)
	v_add_f32_e32 v64, v64, v65
	v_mov_b32_e32 v65, v64
	s_nop 1
	v_permlane32_swap_b32_e32 v64, v65
	v_cvt_pk_bf16_f32 v68, v84, v85
	v_cvt_pk_bf16_f32 v69, v86, v87
	global_store_dwordx4 v[70:71], v[66:69], off
	s_and_saveexec_b64 s[18:19], s[38:39]
	s_cbranch_execz .LBB0_464
	s_waitcnt lgkmcnt(0)
	v_add_f32_e32 v66, v64, v65
	v_lshlrev_b64 v[64:65], 7, v[188:189]
	v_lshl_add_u64 v[64:65], s[14:15], 0, v[64:65]
	v_lshl_add_u64 v[64:65], s[2:3], 2, v[64:65]
	s_lshl_b32 s96, s49, 2
	v_lshl_add_u64 v[64:65], v[64:65], 0, s[96:97]
	global_store_dword v[64:65], v66, off
.LBB0_464:
	s_or_b64 exec, exec, s[18:19]
	v_mul_f32_e32 v48, 0xbfb8aa3b, v48
	v_exp_f32_e32 v48, v48
	v_mul_f32_e32 v49, 0xbfb8aa3b, v49
	v_exp_f32_e32 v49, v49
	v_lshlrev_b32_e32 v68, 16, v142
	v_add_f32_e32 v48, 1.0, v48
	v_rcp_f32_e32 v48, v48
	v_mul_f32_e32 v50, 0xbfb8aa3b, v50
	v_exp_f32_e32 v50, v50
	v_and_b32_e32 v69, 0xffff0000, v142
	v_fmac_f32_e32 v68, v56, v48
	v_add_f32_e32 v48, 1.0, v49
	v_mul_f32_e32 v49, 0xbfb8aa3b, v54
	v_rcp_f32_e32 v48, v48
	v_exp_f32_e32 v49, v49
	v_mul_f32_e32 v53, 0xbfb8aa3b, v53
	v_mul_f32_e32 v52, 0xbfb8aa3b, v52
	v_fmac_f32_e32 v69, v57, v48
	v_add_f32_e32 v48, 1.0, v49
	v_add_f32_e32 v49, 1.0, v50
	v_mul_f32_e32 v50, 0xbfb8aa3b, v55
	v_exp_f32_e32 v53, v53
	v_exp_f32_e32 v50, v50
	v_exp_f32_e32 v52, v52
	v_mul_f32_e32 v51, 0xbfb8aa3b, v51
	v_exp_f32_e32 v51, v51
	v_add_f32_e32 v53, 1.0, v53
	v_add_f32_e32 v50, 1.0, v50
	v_add_f32_e32 v52, 1.0, v52
	v_rcp_f32_e32 v53, v53
	v_rcp_f32_e32 v50, v50
	v_rcp_f32_e32 v52, v52
	v_rcp_f32_e32 v48, v48
	v_rcp_f32_e32 v49, v49
	v_add_f32_e32 v51, 1.0, v51
	v_rcp_f32_e32 v51, v51
	s_waitcnt lgkmcnt(0)
	v_and_b32_e32 v65, 0xffff0000, v140
	v_and_b32_e32 v67, 0xffff0000, v141
	v_lshlrev_b32_e32 v64, 16, v140
	v_lshlrev_b32_e32 v66, 16, v141
	v_lshlrev_b32_e32 v70, 16, v143
	v_fmac_f32_e32 v65, v61, v53
	v_fmac_f32_e32 v67, v63, v50
	v_and_b32_e32 v71, 0xffff0000, v143
	v_fmac_f32_e32 v64, v60, v52
	v_fmac_f32_e32 v66, v62, v48
	v_fmac_f32_e32 v70, v58, v49
	v_mul_f32_e32 v48, v65, v65
	v_mul_f32_e32 v49, v67, v67
	v_fmac_f32_e32 v71, v59, v51
	v_fmac_f32_e32 v48, v64, v64
	v_fmac_f32_e32 v49, v66, v66
	v_add_f32_e32 v48, v48, v49
	v_mul_f32_e32 v49, v69, v69
	v_mul_f32_e32 v50, v71, v71
	v_fmac_f32_e32 v49, v68, v68
	v_fmac_f32_e32 v50, v70, v70
	v_add_f32_e32 v49, v49, v50
	v_add_f32_e32 v48, v48, v49
	v_mov_b32_e32 v49, v48
	s_nop 1
	v_permlane16_swap_b32_e32 v48, v49
	v_lshl_add_u64 v[54:55], s[12:13], 0, v[186:187]
	v_lshl_add_u64 v[54:55], v[170:171], 1, v[54:55]
	v_cvt_pk_bf16_f32 v50, v64, v65
	v_cvt_pk_bf16_f32 v51, v66, v67
	s_waitcnt lgkmcnt(0)
	v_add_f32_e32 v48, v48, v49
	v_mov_b32_e32 v49, v48
	s_nop 1
	v_permlane32_swap_b32_e32 v48, v49
	v_cvt_pk_bf16_f32 v52, v68, v69
	v_cvt_pk_bf16_f32 v53, v70, v71
	global_store_dwordx4 v[54:55], v[50:53], off
	s_and_saveexec_b64 s[18:19], s[38:39]
	s_cbranch_execz .LBB0_466
	s_waitcnt lgkmcnt(0)
	v_add_f32_e32 v50, v48, v49
	v_lshlrev_b64 v[48:49], 7, v[184:185]
	v_lshl_add_u64 v[48:49], s[14:15], 0, v[48:49]
	v_lshl_add_u64 v[48:49], s[2:3], 2, v[48:49]
	s_lshl_b32 s96, s49, 2
	v_lshl_add_u64 v[48:49], v[48:49], 0, s[96:97]
	global_store_dword v[48:49], v50, off
; __device__ __forceinline__ unsigned cvt_pk_bf16(float lo, float hi) { unsigned r; asm volatile("v_cvt_pk_bf16_f32 %0, %1, %2" : "=v"(r) : "v"(lo), "v"(hi)); return r; }
; __device__ __forceinline__ float shx(float v, int lane, int mask) { return __builtin_bit_cast(float, __builtin_amdgcn_ds_bpermute((lane ^ mask) << 2, __builtin_bit_cast(int, v))); }
; __device__ __forceinline__ f32x4 bf_lo4(unsigned a, unsigned b) { return (f32x4){__uint_as_float(a << 16), __uint_as_float(a & 0xffff0000u), __uint_as_float(b << 16), __uint_as_float(b & 0xffff0000u)}; }
;     __device__ __forceinline__ void operator()(AccT& acc, const Unit& u, int wr, int wc, int fr, int fq, PG8_LAS unsigned char*) const {
;     ...
;             for (int m = 0; m < 4; ++m) { const int row = u.pm * BM + ai * HALF + wr * 64 + m * 16 + fr; const size_t off = (size_t)row * 1024 + col0;
;                 const u32x4 bb = bs[ai][m];
;                 f32x4 v0 = bf_lo4(bb.x, bb.y), v1 = bf_lo4(bb.z, bb.w);
;                 const f32x4 a0 = acc[ai][0][m][0], a1 = acc[ai][0][m][1], g0 = acc[ai][1][m][0], g1 = acc[ai][1][m][1];
; #pragma unroll
;                 for (int j = 0; j < 4; ++j) { v0[j] += a0[j] * __builtin_amdgcn_rcpf(1.f + __builtin_amdgcn_exp2f(-1.4426950408889634f * g0[j]));
;                                               v1[j] += a1[j] * __builtin_amdgcn_rcpf(1.f + __builtin_amdgcn_exp2f(-1.4426950408889634f * g1[j])); }
;                 u32x4 w; w.x = cvt_pk_bf16(v0.x, v0.y); w.y = cvt_pk_bf16(v0.z, v0.w); w.z = cvt_pk_bf16(v1.x, v1.y); w.w = cvt_pk_bf16(v1.z, v1.w);
;                 *(u32x4*)(hb + off) = w;
;                 float ss = ((v0.x * v0.x + v0.y * v0.y) + (v0.z * v0.z + v0.w * v0.w)) + ((v1.x * v1.x + v1.y * v1.y) + (v1.z * v1.z + v1.w * v1.w));
;                 ss += shx(ss, lane, 16); ss += shx(ss, lane, 32);
;                 if (fq == 0) ssq[(size_t)row * 32 + u.pn * 4 + wc] = ss; }
.LBB0_466:
	s_or_b64 exec, exec, s[18:19]
	v_mul_f32_e32 v32, 0xbfb8aa3b, v32
	v_exp_f32_e32 v32, v32
	v_mul_f32_e32 v33, 0xbfb8aa3b, v33
	v_exp_f32_e32 v33, v33
	v_lshlrev_b32_e32 v52, 16, v138
	v_add_f32_e32 v32, 1.0, v32
	v_rcp_f32_e32 v32, v32
	v_mul_f32_e32 v34, 0xbfb8aa3b, v34
	v_exp_f32_e32 v34, v34
	v_and_b32_e32 v53, 0xffff0000, v138
	v_fmac_f32_e32 v52, v40, v32
	v_add_f32_e32 v32, 1.0, v33
	v_mul_f32_e32 v33, 0xbfb8aa3b, v38
	v_rcp_f32_e32 v32, v32
	v_exp_f32_e32 v33, v33
	v_mul_f32_e32 v37, 0xbfb8aa3b, v37
	v_mul_f32_e32 v36, 0xbfb8aa3b, v36
	v_fmac_f32_e32 v53, v41, v32
	v_add_f32_e32 v32, 1.0, v33
	v_add_f32_e32 v33, 1.0, v34
	v_mul_f32_e32 v34, 0xbfb8aa3b, v39
	v_exp_f32_e32 v37, v37
	v_exp_f32_e32 v34, v34
	v_exp_f32_e32 v36, v36
	v_mul_f32_e32 v35, 0xbfb8aa3b, v35
	v_exp_f32_e32 v35, v35
	v_add_f32_e32 v37, 1.0, v37
	v_add_f32_e32 v34, 1.0, v34
	v_add_f32_e32 v36, 1.0, v36
	v_rcp_f32_e32 v37, v37
	v_rcp_f32_e32 v34, v34
	v_rcp_f32_e32 v36, v36
	v_rcp_f32_e32 v32, v32
	v_rcp_f32_e32 v33, v33
	v_add_f32_e32 v35, 1.0, v35
	v_rcp_f32_e32 v35, v35
	s_waitcnt lgkmcnt(0)
	v_and_b32_e32 v49, 0xffff0000, v136
	v_and_b32_e32 v51, 0xffff0000, v137
	v_lshlrev_b32_e32 v48, 16, v136
	v_lshlrev_b32_e32 v50, 16, v137
	v_lshlrev_b32_e32 v54, 16, v139
	v_fmac_f32_e32 v49, v45, v37
	v_fmac_f32_e32 v51, v47, v34
	v_and_b32_e32 v55, 0xffff0000, v139
	v_fmac_f32_e32 v48, v44, v36
	v_fmac_f32_e32 v50, v46, v32
	v_fmac_f32_e32 v54, v42, v33
	v_mul_f32_e32 v32, v49, v49
	v_mul_f32_e32 v33, v51, v51
	v_fmac_f32_e32 v55, v43, v35
	v_fmac_f32_e32 v32, v48, v48
	v_fmac_f32_e32 v33, v50, v50
	v_add_f32_e32 v32, v32, v33
	v_mul_f32_e32 v33, v53, v53
	v_mul_f32_e32 v34, v55, v55
	v_fmac_f32_e32 v33, v52, v52
	v_fmac_f32_e32 v34, v54, v54
	v_add_f32_e32 v33, v33, v34
	v_add_f32_e32 v32, v32, v33
	v_mov_b32_e32 v33, v32
	s_nop 1
	v_permlane16_swap_b32_e32 v32, v33
	v_lshl_add_u64 v[38:39], s[12:13], 0, v[182:183]
	v_lshl_add_u64 v[38:39], v[170:171], 1, v[38:39]
	v_cvt_pk_bf16_f32 v34, v48, v49
	v_cvt_pk_bf16_f32 v35, v50, v51
	s_waitcnt lgkmcnt(0)
	v_add_f32_e32 v32, v32, v33
	v_mov_b32_e32 v33, v32
	s_nop 1
	v_permlane32_swap_b32_e32 v32, v33
	v_cvt_pk_bf16_f32 v36, v52, v53
	v_cvt_pk_bf16_f32 v37, v54, v55
	global_store_dwordx4 v[38:39], v[34:37], off
	s_and_saveexec_b64 s[18:19], s[38:39]
	s_cbranch_execz .LBB0_468
	s_waitcnt lgkmcnt(0)
	v_add_f32_e32 v34, v32, v33
	v_lshlrev_b64 v[32:33], 7, v[180:181]
	v_lshl_add_u64 v[32:33], s[14:15], 0, v[32:33]
	v_lshl_add_u64 v[32:33], s[2:3], 2, v[32:33]
	s_lshl_b32 s96, s49, 2
	v_lshl_add_u64 v[32:33], v[32:33], 0, s[96:97]
	global_store_dword v[32:33], v34, off
; __device__ __forceinline__ unsigned cvt_pk_bf16(float lo, float hi) { unsigned r; asm volatile("v_cvt_pk_bf16_f32 %0, %1, %2" : "=v"(r) : "v"(lo), "v"(hi)); return r; }
; __device__ __forceinline__ float shx(float v, int lane, int mask) { return __builtin_bit_cast(float, __builtin_amdgcn_ds_bpermute((lane ^ mask) << 2, __builtin_bit_cast(int, v))); }
; __device__ __forceinline__ f32x4 bf_lo4(unsigned a, unsigned b) { return (f32x4){__uint_as_float(a << 16), __uint_as_float(a & 0xffff0000u), __uint_as_float(b << 16), __uint_as_float(b & 0xffff0000u)}; }
;     __device__ __forceinline__ void operator()(AccT& acc, const Unit& u, int wr, int wc, int fr, int fq, PG8_LAS unsigned char*) const {
;     ...
;             for (int m = 0; m < 4; ++m) { const int row = u.pm * BM + ai * HALF + wr * 64 + m * 16 + fr; const size_t off = (size_t)row * 1024 + col0;
;                 const u32x4 bb = bs[ai][m];
;                 f32x4 v0 = bf_lo4(bb.x, bb.y), v1 = bf_lo4(bb.z, bb.w);
;                 const f32x4 a0 = acc[ai][0][m][0], a1 = acc[ai][0][m][1], g0 = acc[ai][1][m][0], g1 = acc[ai][1][m][1];
; #pragma unroll
;                 for (int j = 0; j < 4; ++j) { v0[j] += a0[j] * __builtin_amdgcn_rcpf(1.f + __builtin_amdgcn_exp2f(-1.4426950408889634f * g0[j]));
;                                               v1[j] += a1[j] * __builtin_amdgcn_rcpf(1.f + __builtin_amdgcn_exp2f(-1.4426950408889634f * g1[j])); }
;                 u32x4 w; w.x = cvt_pk_bf16(v0.x, v0.y); w.y = cvt_pk_bf16(v0.z, v0.w); w.z = cvt_pk_bf16(v1.x, v1.y); w.w = cvt_pk_bf16(v1.z, v1.w);
;                 *(u32x4*)(hb + off) = w;
;                 float ss = ((v0.x * v0.x + v0.y * v0.y) + (v0.z * v0.z + v0.w * v0.w)) + ((v1.x * v1.x + v1.y * v1.y) + (v1.z * v1.z + v1.w * v1.w));
;                 ss += shx(ss, lane, 16); ss += shx(ss, lane, 32);
;                 if (fq == 0) ssq[(size_t)row * 32 + u.pn * 4 + wc] = ss; }
.LBB0_468:
	s_or_b64 exec, exec, s[18:19]
	v_mul_f32_e32 v16, 0xbfb8aa3b, v16
	v_exp_f32_e32 v16, v16
	v_mul_f32_e32 v17, 0xbfb8aa3b, v17
	v_exp_f32_e32 v17, v17
	v_lshlrev_b32_e32 v36, 16, v134
	v_add_f32_e32 v16, 1.0, v16
	v_rcp_f32_e32 v16, v16
	v_mul_f32_e32 v18, 0xbfb8aa3b, v18
	v_exp_f32_e32 v18, v18
	v_and_b32_e32 v37, 0xffff0000, v134
	v_fmac_f32_e32 v36, v24, v16
	v_add_f32_e32 v16, 1.0, v17
	v_mul_f32_e32 v17, 0xbfb8aa3b, v22
	v_rcp_f32_e32 v16, v16
	v_exp_f32_e32 v17, v17
	v_mul_f32_e32 v21, 0xbfb8aa3b, v21
	v_mul_f32_e32 v20, 0xbfb8aa3b, v20
	v_fmac_f32_e32 v37, v25, v16
	v_add_f32_e32 v16, 1.0, v17
	v_add_f32_e32 v17, 1.0, v18
	v_mul_f32_e32 v18, 0xbfb8aa3b, v23
	v_exp_f32_e32 v21, v21
	v_exp_f32_e32 v18, v18
	v_exp_f32_e32 v20, v20
	v_mul_f32_e32 v19, 0xbfb8aa3b, v19
	v_exp_f32_e32 v19, v19
	v_add_f32_e32 v21, 1.0, v21
	v_add_f32_e32 v18, 1.0, v18
	v_add_f32_e32 v20, 1.0, v20
	v_rcp_f32_e32 v21, v21
	v_rcp_f32_e32 v18, v18
	v_rcp_f32_e32 v20, v20
	v_rcp_f32_e32 v16, v16
	v_rcp_f32_e32 v17, v17
	v_add_f32_e32 v19, 1.0, v19
	v_rcp_f32_e32 v19, v19
	s_waitcnt lgkmcnt(0)
	v_and_b32_e32 v33, 0xffff0000, v132
	v_and_b32_e32 v35, 0xffff0000, v133
	v_lshlrev_b32_e32 v32, 16, v132
	v_lshlrev_b32_e32 v34, 16, v133
	v_lshlrev_b32_e32 v38, 16, v135
	v_fmac_f32_e32 v33, v29, v21
	v_fmac_f32_e32 v35, v31, v18
	v_and_b32_e32 v39, 0xffff0000, v135
	v_fmac_f32_e32 v32, v28, v20
	v_fmac_f32_e32 v34, v30, v16
	v_fmac_f32_e32 v38, v26, v17
	v_mul_f32_e32 v16, v33, v33
	v_mul_f32_e32 v17, v35, v35
	v_fmac_f32_e32 v39, v27, v19
	v_fmac_f32_e32 v16, v32, v32
	v_fmac_f32_e32 v17, v34, v34
	v_add_f32_e32 v16, v16, v17
	v_mul_f32_e32 v17, v37, v37
	v_mul_f32_e32 v18, v39, v39
	v_fmac_f32_e32 v17, v36, v36
	v_fmac_f32_e32 v18, v38, v38
	v_add_f32_e32 v17, v17, v18
	v_add_f32_e32 v16, v16, v17
	v_mov_b32_e32 v17, v16
	s_nop 1
	v_permlane16_swap_b32_e32 v16, v17
	v_lshl_add_u64 v[22:23], s[12:13], 0, v[178:179]
	v_lshl_add_u64 v[22:23], v[170:171], 1, v[22:23]
	v_cvt_pk_bf16_f32 v18, v32, v33
	v_cvt_pk_bf16_f32 v19, v34, v35
	s_waitcnt lgkmcnt(0)
	v_add_f32_e32 v16, v16, v17
	v_mov_b32_e32 v17, v16
	s_nop 1
	v_permlane32_swap_b32_e32 v16, v17
	v_cvt_pk_bf16_f32 v20, v36, v37
	v_cvt_pk_bf16_f32 v21, v38, v39
	global_store_dwordx4 v[22:23], v[18:21], off
	s_and_saveexec_b64 s[18:19], s[38:39]
	s_cbranch_execz .LBB0_470
	s_waitcnt lgkmcnt(0)
	v_add_f32_e32 v18, v16, v17
	v_lshlrev_b64 v[16:17], 7, v[176:177]
	v_lshl_add_u64 v[16:17], s[14:15], 0, v[16:17]
	v_lshl_add_u64 v[16:17], s[2:3], 2, v[16:17]
	s_lshl_b32 s96, s49, 2
	v_lshl_add_u64 v[16:17], v[16:17], 0, s[96:97]
	global_store_dword v[16:17], v18, off
.LBB0_470:
	s_or_b64 exec, exec, s[18:19]
	v_mul_f32_e32 v0, 0xbfb8aa3b, v0
	v_exp_f32_e32 v0, v0
	v_mul_f32_e32 v1, 0xbfb8aa3b, v1
	v_exp_f32_e32 v1, v1
	v_lshlrev_b32_e32 v20, 16, v114
	v_add_f32_e32 v0, 1.0, v0
	v_rcp_f32_e32 v0, v0
	v_mul_f32_e32 v2, 0xbfb8aa3b, v2
	v_exp_f32_e32 v2, v2
	v_and_b32_e32 v21, 0xffff0000, v114
	v_fmac_f32_e32 v20, v8, v0
	v_add_f32_e32 v0, 1.0, v1
	v_mul_f32_e32 v1, 0xbfb8aa3b, v6
	v_rcp_f32_e32 v0, v0
	v_exp_f32_e32 v1, v1
	v_mul_f32_e32 v5, 0xbfb8aa3b, v5
	v_mul_f32_e32 v4, 0xbfb8aa3b, v4
	v_fmac_f32_e32 v21, v9, v0
	v_add_f32_e32 v0, 1.0, v1
	v_add_f32_e32 v1, 1.0, v2
	v_mul_f32_e32 v2, 0xbfb8aa3b, v7
	v_exp_f32_e32 v5, v5
	v_exp_f32_e32 v2, v2
	v_exp_f32_e32 v4, v4
	v_mul_f32_e32 v3, 0xbfb8aa3b, v3
	v_exp_f32_e32 v3, v3
	v_add_f32_e32 v5, 1.0, v5
	v_add_f32_e32 v2, 1.0, v2
	v_add_f32_e32 v4, 1.0, v4
	v_rcp_f32_e32 v5, v5
	v_rcp_f32_e32 v2, v2
	v_rcp_f32_e32 v4, v4
	v_rcp_f32_e32 v0, v0
	v_rcp_f32_e32 v1, v1
	v_add_f32_e32 v3, 1.0, v3
	v_rcp_f32_e32 v3, v3
	s_waitcnt lgkmcnt(0)
	v_and_b32_e32 v17, 0xffff0000, v112
	v_and_b32_e32 v19, 0xffff0000, v113
	v_lshlrev_b32_e32 v16, 16, v112
	v_lshlrev_b32_e32 v18, 16, v113
	v_lshlrev_b32_e32 v22, 16, v115
	v_fmac_f32_e32 v17, v13, v5
	v_fmac_f32_e32 v19, v15, v2
	v_and_b32_e32 v23, 0xffff0000, v115
	v_fmac_f32_e32 v16, v12, v4
	v_fmac_f32_e32 v18, v14, v0
	v_fmac_f32_e32 v22, v10, v1
	v_mul_f32_e32 v0, v17, v17
	v_mul_f32_e32 v1, v19, v19
	v_fmac_f32_e32 v23, v11, v3
	v_fmac_f32_e32 v0, v16, v16
	v_fmac_f32_e32 v1, v18, v18
	v_add_f32_e32 v0, v0, v1
	v_mul_f32_e32 v1, v21, v21
	v_mul_f32_e32 v2, v23, v23
	v_fmac_f32_e32 v1, v20, v20
	v_fmac_f32_e32 v2, v22, v22
	v_add_f32_e32 v1, v1, v2
	v_add_f32_e32 v0, v0, v1
	v_mov_b32_e32 v1, v0
	s_nop 1
	v_permlane16_swap_b32_e32 v0, v1
	v_lshl_add_u64 v[6:7], s[12:13], 0, v[174:175]
	v_lshl_add_u64 v[6:7], v[170:171], 1, v[6:7]
	v_cvt_pk_bf16_f32 v2, v16, v17
	v_cvt_pk_bf16_f32 v3, v18, v19
	s_waitcnt lgkmcnt(0)
	v_add_f32_e32 v0, v0, v1
	v_mov_b32_e32 v1, v0
	s_nop 1
	v_permlane32_swap_b32_e32 v0, v1
	v_cvt_pk_bf16_f32 v4, v20, v21
	v_cvt_pk_bf16_f32 v5, v22, v23
	global_store_dwordx4 v[6:7], v[2:5], off
	s_and_saveexec_b64 s[18:19], s[38:39]
	s_cbranch_execz .LBB0_475
	s_waitcnt lgkmcnt(0)
	v_add_f32_e32 v2, v0, v1
	v_lshlrev_b64 v[0:1], 7, v[172:173]
	v_lshl_add_u64 v[0:1], s[14:15], 0, v[0:1]
	v_lshl_add_u64 v[0:1], s[2:3], 2, v[0:1]
	s_lshl_b32 s96, s49, 2
	v_lshl_add_u64 v[0:1], v[0:1], 0, s[96:97]
	global_store_dword v[0:1], v2, off
	s_or_b64 exec, exec, s[18:19]
	s_andn2_b64 vcc, exec, s[40:41]
	s_mov_b64 s[2:3], -1
	s_cbranch_vccz .LBB0_476

; __device__ __forceinline__ unsigned cvt_pk_bf16(float lo, float hi) { unsigned r; asm volatile("v_cvt_pk_bf16_f32 %0, %1, %2" : "=v"(r) : "v"(lo), "v"(hi)); return r; }
; __device__ __forceinline__ float shx(float v, int lane, int mask) { return __builtin_bit_cast(float, __builtin_amdgcn_ds_bpermute((lane ^ mask) << 2, __builtin_bit_cast(int, v))); }
; __device__ __forceinline__ f32x4 bf_lo4(unsigned a, unsigned b) { return (f32x4){__uint_as_float(a << 16), __uint_as_float(a & 0xffff0000u), __uint_as_float(b << 16), __uint_as_float(b & 0xffff0000u)}; }
;     __device__ __forceinline__ void operator()(AccT& acc, const Unit& u, int wr, int wc, int fr, int fq, PG8_LAS unsigned char*) const {
;     ...
;                     const f32x4 v0 = acc[ai][bj][m][0] + bf_lo4(bb.x, bb.y), v1 = acc[ai][bj][m][1] + bf_lo4(bb.z, bb.w);
;                     u32x4 w; w.x = cvt_pk_bf16(v0.x, v0.y); w.y = cvt_pk_bf16(v0.z, v0.w); w.z = cvt_pk_bf16(v1.x, v1.y); w.w = cvt_pk_bf16(v1.z, v1.w);
;                     if (fout) { float* fo = (float*)((char*)fout + (size_t)(e + bj * HALF) * 4u); *(f32x4*)fo = v0; *(f32x4*)(fo + 4) = v1; }
;                     else {
;                         *(u32x4*)((char*)hb + ((e + bj * HALF) * 2u)) = w;
;                         float ss = ((v0.x * v0.x + v0.y * v0.y) + (v0.z * v0.z + v0.w * v0.w)) + ((v1.x * v1.x + v1.y * v1.y) + (v1.z * v1.z + v1.w * v1.w));
;                         ss += shx(ss, lane, 16); ss += shx(ss, lane, 32);
;                         if (fq == 0) ssq[(size_t)row * 32 + u.pn * 8 + bj * 4 + wc] = ss; } } }
.LBB0_544:
	s_lshl_b32 s0, s58, 3
	v_ashrrev_i32_e32 v219, 31, v218
	s_ashr_i32 s1, s0, 31
	v_lshlrev_b32_e32 v244, 1, v208
	s_andn2_b64 vcc, exec, s[2:3]
	v_lshlrev_b64 v[220:221], 7, v[218:219]
	s_cbranch_vccnz .LBB0_548
	v_mul_f32_e32 v165, v165, v165
	v_mul_f32_e32 v161, v161, v161
	v_fmac_f32_e32 v165, v164, v164
	v_mul_f32_e32 v164, v167, v167
	v_fmac_f32_e32 v161, v160, v160
	v_mul_f32_e32 v160, v163, v163
	v_fmac_f32_e32 v164, v166, v166
	v_fmac_f32_e32 v160, v162, v162
	v_add_f32_e32 v164, v165, v164
	v_add_f32_e32 v160, v161, v160
	v_add_f32_e32 v160, v164, v160
	v_mov_b32_e32 v161, v160
	s_nop 1
	v_permlane16_swap_b32_e32 v160, v161
	global_store_dwordx4 v244, v[188:191], s[8:9]
	s_waitcnt lgkmcnt(0)
	v_add_f32_e32 v160, v160, v161
	v_mov_b32_e32 v161, v160
	s_nop 1
	v_permlane32_swap_b32_e32 v160, v161
	s_and_saveexec_b64 s[2:3], s[36:37]
	s_cbranch_execz .LBB0_547
	v_lshl_add_u64 v[162:163], s[10:11], 0, v[220:221]
	v_lshl_add_u64 v[162:163], s[0:1], 2, v[162:163]
	s_lshl_b32 s96, s49, 2
	v_lshl_add_u64 v[162:163], v[162:163], 0, s[96:97]
	s_waitcnt lgkmcnt(0)
	v_add_f32_e32 v160, v160, v161
	global_store_dword v[162:163], v160, off

; __device__ __forceinline__ unsigned cvt_pk_bf16(float lo, float hi) { unsigned r; asm volatile("v_cvt_pk_bf16_f32 %0, %1, %2" : "=v"(r) : "v"(lo), "v"(hi)); return r; }
; __device__ __forceinline__ float shx(float v, int lane, int mask) { return __builtin_bit_cast(float, __builtin_amdgcn_ds_bpermute((lane ^ mask) << 2, __builtin_bit_cast(int, v))); }
; __device__ __forceinline__ f32x4 bf_lo4(unsigned a, unsigned b) { return (f32x4){__uint_as_float(a << 16), __uint_as_float(a & 0xffff0000u), __uint_as_float(b << 16), __uint_as_float(b & 0xffff0000u)}; }
;     __device__ __forceinline__ void operator()(AccT& acc, const Unit& u, int wr, int wc, int fr, int fq, PG8_LAS unsigned char*) const {
;     ...
;                     const f32x4 v0 = acc[ai][bj][m][0] + bf_lo4(bb.x, bb.y), v1 = acc[ai][bj][m][1] + bf_lo4(bb.z, bb.w);
;                     u32x4 w; w.x = cvt_pk_bf16(v0.x, v0.y); w.y = cvt_pk_bf16(v0.z, v0.w); w.z = cvt_pk_bf16(v1.x, v1.y); w.w = cvt_pk_bf16(v1.z, v1.w);
;                     if (fout) { float* fo = (float*)((char*)fout + (size_t)(e + bj * HALF) * 4u); *(f32x4*)fo = v0; *(f32x4*)(fo + 4) = v1; }
;                     else {
;                         *(u32x4*)((char*)hb + ((e + bj * HALF) * 2u)) = w;
;                         float ss = ((v0.x * v0.x + v0.y * v0.y) + (v0.z * v0.z + v0.w * v0.w)) + ((v1.x * v1.x + v1.y * v1.y) + (v1.z * v1.z + v1.w * v1.w));
;                         ss += shx(ss, lane, 16); ss += shx(ss, lane, 32);
;                         if (fq == 0) ssq[(size_t)row * 32 + u.pn * 8 + bj * 4 + wc] = ss; } } }
.LBB0_550:
.LBB0_551:
	v_mul_f32_e32 v149, v149, v149
	v_mul_f32_e32 v141, v141, v141
	v_fmac_f32_e32 v149, v148, v148
	v_mul_f32_e32 v148, v151, v151
	v_fmac_f32_e32 v141, v140, v140
	v_mul_f32_e32 v140, v143, v143
	v_fmac_f32_e32 v148, v150, v150
	v_fmac_f32_e32 v140, v142, v142
	v_add_f32_e32 v148, v149, v148
	v_add_f32_e32 v140, v141, v140
	v_add_f32_e32 v140, v148, v140
	v_mov_b32_e32 v141, v140
	s_nop 1
	v_permlane16_swap_b32_e32 v140, v141
	v_or_b32_e32 v142, 0x100, v244
	global_store_dwordx4 v142, v[160:163], s[8:9]
	s_waitcnt lgkmcnt(0)
	v_add_f32_e32 v140, v140, v141
	v_mov_b32_e32 v141, v140
	s_nop 1
	v_permlane32_swap_b32_e32 v140, v141
	s_and_saveexec_b64 s[2:3], s[36:37]
	s_cbranch_execz .LBB0_553
	v_lshl_add_u64 v[142:143], s[10:11], 0, v[220:221]
	v_lshl_add_u64 v[142:143], s[0:1], 2, v[142:143]
	s_lshl_b32 s96, s49, 2
	v_lshl_add_u64 v[142:143], v[142:143], 0, s[96:97]
	s_waitcnt lgkmcnt(0)
	v_add_f32_e32 v140, v140, v141
	global_store_dword v[142:143], v140, off offset:16

; __device__ __forceinline__ unsigned cvt_pk_bf16(float lo, float hi) { unsigned r; asm volatile("v_cvt_pk_bf16_f32 %0, %1, %2" : "=v"(r) : "v"(lo), "v"(hi)); return r; }
; __device__ __forceinline__ float shx(float v, int lane, int mask) { return __builtin_bit_cast(float, __builtin_amdgcn_ds_bpermute((lane ^ mask) << 2, __builtin_bit_cast(int, v))); }
; __device__ __forceinline__ f32x4 bf_lo4(unsigned a, unsigned b) { return (f32x4){__uint_as_float(a << 16), __uint_as_float(a & 0xffff0000u), __uint_as_float(b << 16), __uint_as_float(b & 0xffff0000u)}; }
;     __device__ __forceinline__ void operator()(AccT& acc, const Unit& u, int wr, int wc, int fr, int fq, PG8_LAS unsigned char*) const {
;     ...
;                     const f32x4 v0 = acc[ai][bj][m][0] + bf_lo4(bb.x, bb.y), v1 = acc[ai][bj][m][1] + bf_lo4(bb.z, bb.w);
;                     u32x4 w; w.x = cvt_pk_bf16(v0.x, v0.y); w.y = cvt_pk_bf16(v0.z, v0.w); w.z = cvt_pk_bf16(v1.x, v1.y); w.w = cvt_pk_bf16(v1.z, v1.w);
;                     if (fout) { float* fo = (float*)((char*)fout + (size_t)(e + bj * HALF) * 4u); *(f32x4*)fo = v0; *(f32x4*)(fo + 4) = v1; }
;                     else {
;                         *(u32x4*)((char*)hb + ((e + bj * HALF) * 2u)) = w;
;                         float ss = ((v0.x * v0.x + v0.y * v0.y) + (v0.z * v0.z + v0.w * v0.w)) + ((v1.x * v1.x + v1.y * v1.y) + (v1.z * v1.z + v1.w * v1.w));
;                         ss += shx(ss, lane, 16); ss += shx(ss, lane, 32);
;                         if (fq == 0) ssq[(size_t)row * 32 + u.pn * 8 + bj * 4 + wc] = ss; } } }
.LBB0_557:
	v_ashrrev_i32_e32 v149, 31, v148
	v_lshlrev_b32_e32 v150, 1, v208
	s_andn2_b64 vcc, exec, s[2:3]
	v_lshlrev_b64 v[148:149], 7, v[148:149]
	s_cbranch_vccnz .LBB0_561
	v_mul_f32_e32 v137, v137, v137
	v_mul_f32_e32 v133, v133, v133
	v_fmac_f32_e32 v137, v136, v136
	v_mul_f32_e32 v136, v139, v139
	v_fmac_f32_e32 v133, v132, v132
	v_mul_f32_e32 v132, v135, v135
	v_fmac_f32_e32 v136, v138, v138
	v_fmac_f32_e32 v132, v134, v134
	v_add_f32_e32 v136, v137, v136
	v_add_f32_e32 v132, v133, v132
	v_add_f32_e32 v132, v136, v132
	v_mov_b32_e32 v133, v132
	s_nop 1
	v_permlane16_swap_b32_e32 v132, v133
	global_store_dwordx4 v150, v[140:143], s[8:9]
	s_waitcnt lgkmcnt(0)
	v_add_f32_e32 v132, v132, v133
	v_mov_b32_e32 v133, v132
	s_nop 1
	v_permlane32_swap_b32_e32 v132, v133
	s_and_saveexec_b64 s[2:3], s[36:37]
	s_cbranch_execz .LBB0_560
	v_lshl_add_u64 v[134:135], s[10:11], 0, v[148:149]
	v_lshl_add_u64 v[134:135], s[0:1], 2, v[134:135]
	s_lshl_b32 s96, s49, 2
	v_lshl_add_u64 v[134:135], v[134:135], 0, s[96:97]
	s_waitcnt lgkmcnt(0)
	v_add_f32_e32 v132, v132, v133
	global_store_dword v[134:135], v132, off

; __device__ __forceinline__ unsigned cvt_pk_bf16(float lo, float hi) { unsigned r; asm volatile("v_cvt_pk_bf16_f32 %0, %1, %2" : "=v"(r) : "v"(lo), "v"(hi)); return r; }
; __device__ __forceinline__ float shx(float v, int lane, int mask) { return __builtin_bit_cast(float, __builtin_amdgcn_ds_bpermute((lane ^ mask) << 2, __builtin_bit_cast(int, v))); }
; __device__ __forceinline__ f32x4 bf_lo4(unsigned a, unsigned b) { return (f32x4){__uint_as_float(a << 16), __uint_as_float(a & 0xffff0000u), __uint_as_float(b << 16), __uint_as_float(b & 0xffff0000u)}; }
;     __device__ __forceinline__ void operator()(AccT& acc, const Unit& u, int wr, int wc, int fr, int fq, PG8_LAS unsigned char*) const {
;     ...
;                     const f32x4 v0 = acc[ai][bj][m][0] + bf_lo4(bb.x, bb.y), v1 = acc[ai][bj][m][1] + bf_lo4(bb.z, bb.w);
;                     u32x4 w; w.x = cvt_pk_bf16(v0.x, v0.y); w.y = cvt_pk_bf16(v0.z, v0.w); w.z = cvt_pk_bf16(v1.x, v1.y); w.w = cvt_pk_bf16(v1.z, v1.w);
;                     if (fout) { float* fo = (float*)((char*)fout + (size_t)(e + bj * HALF) * 4u); *(f32x4*)fo = v0; *(f32x4*)(fo + 4) = v1; }
;                     else {
;                         *(u32x4*)((char*)hb + ((e + bj * HALF) * 2u)) = w;
;                         float ss = ((v0.x * v0.x + v0.y * v0.y) + (v0.z * v0.z + v0.w * v0.w)) + ((v1.x * v1.x + v1.y * v1.y) + (v1.z * v1.z + v1.w * v1.w));
;                         ss += shx(ss, lane, 16); ss += shx(ss, lane, 32);
;                         if (fq == 0) ssq[(size_t)row * 32 + u.pn * 8 + bj * 4 + wc] = ss; } } }
.LBB0_563:
.LBB0_564:
	v_mul_f32_e32 v121, v121, v121
	v_mul_f32_e32 v117, v117, v117
	v_fmac_f32_e32 v121, v120, v120
	v_mul_f32_e32 v120, v123, v123
	v_fmac_f32_e32 v117, v116, v116
	v_mul_f32_e32 v116, v119, v119
	v_fmac_f32_e32 v120, v122, v122
	v_fmac_f32_e32 v116, v118, v118
	v_add_f32_e32 v120, v121, v120
	v_add_f32_e32 v116, v117, v116
	v_add_f32_e32 v116, v120, v116
	v_mov_b32_e32 v117, v116
	s_nop 1
	v_permlane16_swap_b32_e32 v116, v117
	v_or_b32_e32 v118, 0x100, v150
	global_store_dwordx4 v118, v[132:135], s[8:9]
	s_waitcnt lgkmcnt(0)
	v_add_f32_e32 v116, v116, v117
	v_mov_b32_e32 v117, v116
	s_nop 1
	v_permlane32_swap_b32_e32 v116, v117
	s_and_saveexec_b64 s[2:3], s[36:37]
	s_cbranch_execz .LBB0_566
	v_lshl_add_u64 v[118:119], s[10:11], 0, v[148:149]
	v_lshl_add_u64 v[118:119], s[0:1], 2, v[118:119]
	s_lshl_b32 s96, s49, 2
	v_lshl_add_u64 v[118:119], v[118:119], 0, s[96:97]
	s_waitcnt lgkmcnt(0)
	v_add_f32_e32 v116, v116, v117
	global_store_dword v[118:119], v116, off offset:16

; __device__ __forceinline__ unsigned cvt_pk_bf16(float lo, float hi) { unsigned r; asm volatile("v_cvt_pk_bf16_f32 %0, %1, %2" : "=v"(r) : "v"(lo), "v"(hi)); return r; }
; __device__ __forceinline__ float shx(float v, int lane, int mask) { return __builtin_bit_cast(float, __builtin_amdgcn_ds_bpermute((lane ^ mask) << 2, __builtin_bit_cast(int, v))); }
; __device__ __forceinline__ f32x4 bf_lo4(unsigned a, unsigned b) { return (f32x4){__uint_as_float(a << 16), __uint_as_float(a & 0xffff0000u), __uint_as_float(b << 16), __uint_as_float(b & 0xffff0000u)}; }
;     __device__ __forceinline__ void operator()(AccT& acc, const Unit& u, int wr, int wc, int fr, int fq, PG8_LAS unsigned char*) const {
;     ...
;                     const f32x4 v0 = acc[ai][bj][m][0] + bf_lo4(bb.x, bb.y), v1 = acc[ai][bj][m][1] + bf_lo4(bb.z, bb.w);
;                     u32x4 w; w.x = cvt_pk_bf16(v0.x, v0.y); w.y = cvt_pk_bf16(v0.z, v0.w); w.z = cvt_pk_bf16(v1.x, v1.y); w.w = cvt_pk_bf16(v1.z, v1.w);
;                     if (fout) { float* fo = (float*)((char*)fout + (size_t)(e + bj * HALF) * 4u); *(f32x4*)fo = v0; *(f32x4*)(fo + 4) = v1; }
;                     else {
;                         *(u32x4*)((char*)hb + ((e + bj * HALF) * 2u)) = w;
;                         float ss = ((v0.x * v0.x + v0.y * v0.y) + (v0.z * v0.z + v0.w * v0.w)) + ((v1.x * v1.x + v1.y * v1.y) + (v1.z * v1.z + v1.w * v1.w));
;                         ss += shx(ss, lane, 16); ss += shx(ss, lane, 32);
;                         if (fq == 0) ssq[(size_t)row * 32 + u.pn * 8 + bj * 4 + wc] = ss; } } }
.LBB0_570:
	v_ashrrev_i32_e32 v121, 31, v120
	v_lshlrev_b32_e32 v122, 1, v208
	s_andn2_b64 vcc, exec, s[2:3]
	v_lshlrev_b64 v[120:121], 7, v[120:121]
	s_cbranch_vccnz .LBB0_574
	v_mul_f32_e32 v113, v113, v113
	v_mul_f32_e32 v105, v105, v105
	v_fmac_f32_e32 v113, v112, v112
	v_mul_f32_e32 v112, v115, v115
	v_fmac_f32_e32 v105, v104, v104
	v_mul_f32_e32 v104, v107, v107
	v_fmac_f32_e32 v112, v114, v114
	v_fmac_f32_e32 v104, v106, v106
	v_add_f32_e32 v112, v113, v112
	v_add_f32_e32 v104, v105, v104
	v_add_f32_e32 v104, v112, v104
	v_mov_b32_e32 v105, v104
	s_nop 1
	v_permlane16_swap_b32_e32 v104, v105
	global_store_dwordx4 v122, v[116:119], s[8:9]
	s_waitcnt lgkmcnt(0)
	v_add_f32_e32 v104, v104, v105
	v_mov_b32_e32 v105, v104
	s_nop 1
	v_permlane32_swap_b32_e32 v104, v105
	s_and_saveexec_b64 s[2:3], s[36:37]
	s_cbranch_execz .LBB0_573
	v_lshl_add_u64 v[106:107], s[10:11], 0, v[120:121]
	v_lshl_add_u64 v[106:107], s[0:1], 2, v[106:107]
	s_lshl_b32 s96, s49, 2
	v_lshl_add_u64 v[106:107], v[106:107], 0, s[96:97]
	s_waitcnt lgkmcnt(0)
	v_add_f32_e32 v104, v104, v105
	global_store_dword v[106:107], v104, off

; __device__ __forceinline__ unsigned cvt_pk_bf16(float lo, float hi) { unsigned r; asm volatile("v_cvt_pk_bf16_f32 %0, %1, %2" : "=v"(r) : "v"(lo), "v"(hi)); return r; }
; __device__ __forceinline__ float shx(float v, int lane, int mask) { return __builtin_bit_cast(float, __builtin_amdgcn_ds_bpermute((lane ^ mask) << 2, __builtin_bit_cast(int, v))); }
; __device__ __forceinline__ f32x4 bf_lo4(unsigned a, unsigned b) { return (f32x4){__uint_as_float(a << 16), __uint_as_float(a & 0xffff0000u), __uint_as_float(b << 16), __uint_as_float(b & 0xffff0000u)}; }
;     __device__ __forceinline__ void operator()(AccT& acc, const Unit& u, int wr, int wc, int fr, int fq, PG8_LAS unsigned char*) const {
;     ...
;                     const f32x4 v0 = acc[ai][bj][m][0] + bf_lo4(bb.x, bb.y), v1 = acc[ai][bj][m][1] + bf_lo4(bb.z, bb.w);
;                     u32x4 w; w.x = cvt_pk_bf16(v0.x, v0.y); w.y = cvt_pk_bf16(v0.z, v0.w); w.z = cvt_pk_bf16(v1.x, v1.y); w.w = cvt_pk_bf16(v1.z, v1.w);
;                     if (fout) { float* fo = (float*)((char*)fout + (size_t)(e + bj * HALF) * 4u); *(f32x4*)fo = v0; *(f32x4*)(fo + 4) = v1; }
;                     else {
;                         *(u32x4*)((char*)hb + ((e + bj * HALF) * 2u)) = w;
;                         float ss = ((v0.x * v0.x + v0.y * v0.y) + (v0.z * v0.z + v0.w * v0.w)) + ((v1.x * v1.x + v1.y * v1.y) + (v1.z * v1.z + v1.w * v1.w));
;                         ss += shx(ss, lane, 16); ss += shx(ss, lane, 32);
;                         if (fq == 0) ssq[(size_t)row * 32 + u.pn * 8 + bj * 4 + wc] = ss; } } }
.LBB0_576:
.LBB0_577:
	v_mul_f32_e32 v97, v97, v97
	v_mul_f32_e32 v93, v93, v93
	v_fmac_f32_e32 v97, v96, v96
	v_mul_f32_e32 v96, v99, v99
	v_fmac_f32_e32 v93, v92, v92
	v_mul_f32_e32 v92, v95, v95
	v_fmac_f32_e32 v96, v98, v98
	v_fmac_f32_e32 v92, v94, v94
	v_add_f32_e32 v96, v97, v96
	v_add_f32_e32 v92, v93, v92
	v_add_f32_e32 v92, v96, v92
	v_mov_b32_e32 v93, v92
	s_nop 1
	v_permlane16_swap_b32_e32 v92, v93
	v_or_b32_e32 v94, 0x100, v122
	global_store_dwordx4 v94, v[104:107], s[8:9]
	s_waitcnt lgkmcnt(0)
	v_add_f32_e32 v92, v92, v93
	v_mov_b32_e32 v93, v92
	s_nop 1
	v_permlane32_swap_b32_e32 v92, v93
	s_and_saveexec_b64 s[2:3], s[36:37]
	s_cbranch_execz .LBB0_579
	v_lshl_add_u64 v[94:95], s[10:11], 0, v[120:121]
	v_lshl_add_u64 v[94:95], s[0:1], 2, v[94:95]
	s_lshl_b32 s96, s49, 2
	v_lshl_add_u64 v[94:95], v[94:95], 0, s[96:97]
	s_waitcnt lgkmcnt(0)
	v_add_f32_e32 v92, v92, v93
	global_store_dword v[94:95], v92, off offset:16

; __device__ __forceinline__ unsigned cvt_pk_bf16(float lo, float hi) { unsigned r; asm volatile("v_cvt_pk_bf16_f32 %0, %1, %2" : "=v"(r) : "v"(lo), "v"(hi)); return r; }
; __device__ __forceinline__ float shx(float v, int lane, int mask) { return __builtin_bit_cast(float, __builtin_amdgcn_ds_bpermute((lane ^ mask) << 2, __builtin_bit_cast(int, v))); }
; __device__ __forceinline__ f32x4 bf_lo4(unsigned a, unsigned b) { return (f32x4){__uint_as_float(a << 16), __uint_as_float(a & 0xffff0000u), __uint_as_float(b << 16), __uint_as_float(b & 0xffff0000u)}; }
;     __device__ __forceinline__ void operator()(AccT& acc, const Unit& u, int wr, int wc, int fr, int fq, PG8_LAS unsigned char*) const {
;     ...
;                     const f32x4 v0 = acc[ai][bj][m][0] + bf_lo4(bb.x, bb.y), v1 = acc[ai][bj][m][1] + bf_lo4(bb.z, bb.w);
;                     u32x4 w; w.x = cvt_pk_bf16(v0.x, v0.y); w.y = cvt_pk_bf16(v0.z, v0.w); w.z = cvt_pk_bf16(v1.x, v1.y); w.w = cvt_pk_bf16(v1.z, v1.w);
;                     if (fout) { float* fo = (float*)((char*)fout + (size_t)(e + bj * HALF) * 4u); *(f32x4*)fo = v0; *(f32x4*)(fo + 4) = v1; }
;                     else {
;                         *(u32x4*)((char*)hb + ((e + bj * HALF) * 2u)) = w;
;                         float ss = ((v0.x * v0.x + v0.y * v0.y) + (v0.z * v0.z + v0.w * v0.w)) + ((v1.x * v1.x + v1.y * v1.y) + (v1.z * v1.z + v1.w * v1.w));
;                         ss += shx(ss, lane, 16); ss += shx(ss, lane, 32);
;                         if (fq == 0) ssq[(size_t)row * 32 + u.pn * 8 + bj * 4 + wc] = ss; } } }
.LBB0_583:
	v_ashrrev_i32_e32 v97, 31, v96
	v_lshlrev_b32_e32 v98, 1, v208
	s_andn2_b64 vcc, exec, s[2:3]
	v_lshlrev_b64 v[96:97], 7, v[96:97]
	s_cbranch_vccnz .LBB0_587
	v_mul_f32_e32 v85, v85, v85
	v_mul_f32_e32 v81, v81, v81
	v_fmac_f32_e32 v85, v84, v84
	v_mul_f32_e32 v84, v87, v87
	v_fmac_f32_e32 v81, v80, v80
	v_mul_f32_e32 v80, v83, v83
	v_fmac_f32_e32 v84, v86, v86
	v_fmac_f32_e32 v80, v82, v82
	v_add_f32_e32 v84, v85, v84
	v_add_f32_e32 v80, v81, v80
	v_add_f32_e32 v80, v84, v80
	v_mov_b32_e32 v81, v80
	s_nop 1
	v_permlane16_swap_b32_e32 v80, v81
	global_store_dwordx4 v98, v[92:95], s[8:9]
	s_waitcnt lgkmcnt(0)
	v_add_f32_e32 v80, v80, v81
	v_mov_b32_e32 v81, v80
	s_nop 1
	v_permlane32_swap_b32_e32 v80, v81
	s_and_saveexec_b64 s[2:3], s[36:37]
	s_cbranch_execz .LBB0_586
	v_lshl_add_u64 v[82:83], s[10:11], 0, v[96:97]
	v_lshl_add_u64 v[82:83], s[0:1], 2, v[82:83]
	s_lshl_b32 s96, s49, 2
	v_lshl_add_u64 v[82:83], v[82:83], 0, s[96:97]
	s_waitcnt lgkmcnt(0)
	v_add_f32_e32 v80, v80, v81
	global_store_dword v[82:83], v80, off

; __device__ __forceinline__ unsigned cvt_pk_bf16(float lo, float hi) { unsigned r; asm volatile("v_cvt_pk_bf16_f32 %0, %1, %2" : "=v"(r) : "v"(lo), "v"(hi)); return r; }
; __device__ __forceinline__ float shx(float v, int lane, int mask) { return __builtin_bit_cast(float, __builtin_amdgcn_ds_bpermute((lane ^ mask) << 2, __builtin_bit_cast(int, v))); }
; __device__ __forceinline__ f32x4 bf_lo4(unsigned a, unsigned b) { return (f32x4){__uint_as_float(a << 16), __uint_as_float(a & 0xffff0000u), __uint_as_float(b << 16), __uint_as_float(b & 0xffff0000u)}; }
;     __device__ __forceinline__ void operator()(AccT& acc, const Unit& u, int wr, int wc, int fr, int fq, PG8_LAS unsigned char*) const {
;     ...
;                     const f32x4 v0 = acc[ai][bj][m][0] + bf_lo4(bb.x, bb.y), v1 = acc[ai][bj][m][1] + bf_lo4(bb.z, bb.w);
;                     u32x4 w; w.x = cvt_pk_bf16(v0.x, v0.y); w.y = cvt_pk_bf16(v0.z, v0.w); w.z = cvt_pk_bf16(v1.x, v1.y); w.w = cvt_pk_bf16(v1.z, v1.w);
;                     if (fout) { float* fo = (float*)((char*)fout + (size_t)(e + bj * HALF) * 4u); *(f32x4*)fo = v0; *(f32x4*)(fo + 4) = v1; }
;                     else {
;                         *(u32x4*)((char*)hb + ((e + bj * HALF) * 2u)) = w;
;                         float ss = ((v0.x * v0.x + v0.y * v0.y) + (v0.z * v0.z + v0.w * v0.w)) + ((v1.x * v1.x + v1.y * v1.y) + (v1.z * v1.z + v1.w * v1.w));
;                         ss += shx(ss, lane, 16); ss += shx(ss, lane, 32);
;                         if (fq == 0) ssq[(size_t)row * 32 + u.pn * 8 + bj * 4 + wc] = ss; } } }
.LBB0_589:
.LBB0_590:
	v_mul_f32_e32 v73, v73, v73
	v_mul_f32_e32 v69, v69, v69
	v_fmac_f32_e32 v73, v72, v72
	v_mul_f32_e32 v72, v75, v75
	v_fmac_f32_e32 v69, v68, v68
	v_mul_f32_e32 v68, v71, v71
	v_fmac_f32_e32 v72, v74, v74
	v_fmac_f32_e32 v68, v70, v70
	v_add_f32_e32 v72, v73, v72
	v_add_f32_e32 v68, v69, v68
	v_add_f32_e32 v68, v72, v68
	v_mov_b32_e32 v69, v68
	s_nop 1
	v_permlane16_swap_b32_e32 v68, v69
	v_or_b32_e32 v70, 0x100, v98
	global_store_dwordx4 v70, v[80:83], s[8:9]
	s_waitcnt lgkmcnt(0)
	v_add_f32_e32 v68, v68, v69
	v_mov_b32_e32 v69, v68
	s_nop 1
	v_permlane32_swap_b32_e32 v68, v69
	s_and_saveexec_b64 s[2:3], s[36:37]
	s_cbranch_execz .LBB0_592
	v_lshl_add_u64 v[70:71], s[10:11], 0, v[96:97]
	v_lshl_add_u64 v[70:71], s[0:1], 2, v[70:71]
	s_lshl_b32 s96, s49, 2
	v_lshl_add_u64 v[70:71], v[70:71], 0, s[96:97]
	s_waitcnt lgkmcnt(0)
	v_add_f32_e32 v68, v68, v69
	global_store_dword v[70:71], v68, off offset:16

; __device__ __forceinline__ unsigned cvt_pk_bf16(float lo, float hi) { unsigned r; asm volatile("v_cvt_pk_bf16_f32 %0, %1, %2" : "=v"(r) : "v"(lo), "v"(hi)); return r; }
; __device__ __forceinline__ float shx(float v, int lane, int mask) { return __builtin_bit_cast(float, __builtin_amdgcn_ds_bpermute((lane ^ mask) << 2, __builtin_bit_cast(int, v))); }
; __device__ __forceinline__ f32x4 bf_lo4(unsigned a, unsigned b) { return (f32x4){__uint_as_float(a << 16), __uint_as_float(a & 0xffff0000u), __uint_as_float(b << 16), __uint_as_float(b & 0xffff0000u)}; }
;     __device__ __forceinline__ void operator()(AccT& acc, const Unit& u, int wr, int wc, int fr, int fq, PG8_LAS unsigned char*) const {
;     ...
;                     const f32x4 v0 = acc[ai][bj][m][0] + bf_lo4(bb.x, bb.y), v1 = acc[ai][bj][m][1] + bf_lo4(bb.z, bb.w);
;                     u32x4 w; w.x = cvt_pk_bf16(v0.x, v0.y); w.y = cvt_pk_bf16(v0.z, v0.w); w.z = cvt_pk_bf16(v1.x, v1.y); w.w = cvt_pk_bf16(v1.z, v1.w);
;                     if (fout) { float* fo = (float*)((char*)fout + (size_t)(e + bj * HALF) * 4u); *(f32x4*)fo = v0; *(f32x4*)(fo + 4) = v1; }
;                     else {
;                         *(u32x4*)((char*)hb + ((e + bj * HALF) * 2u)) = w;
;                         float ss = ((v0.x * v0.x + v0.y * v0.y) + (v0.z * v0.z + v0.w * v0.w)) + ((v1.x * v1.x + v1.y * v1.y) + (v1.z * v1.z + v1.w * v1.w));
;                         ss += shx(ss, lane, 16); ss += shx(ss, lane, 32);
;                         if (fq == 0) ssq[(size_t)row * 32 + u.pn * 8 + bj * 4 + wc] = ss; } } }
.LBB0_596:
	v_ashrrev_i32_e32 v73, 31, v72
	v_lshlrev_b32_e32 v74, 1, v208
	s_andn2_b64 vcc, exec, s[2:3]
	v_lshlrev_b64 v[72:73], 7, v[72:73]
	s_cbranch_vccnz .LBB0_600
	v_mul_f32_e32 v61, v61, v61
	v_mul_f32_e32 v57, v57, v57
	v_fmac_f32_e32 v61, v60, v60
	v_mul_f32_e32 v60, v63, v63
	v_fmac_f32_e32 v57, v56, v56
	v_mul_f32_e32 v56, v59, v59
	v_fmac_f32_e32 v60, v62, v62
	v_fmac_f32_e32 v56, v58, v58
	v_add_f32_e32 v60, v61, v60
	v_add_f32_e32 v56, v57, v56
	v_add_f32_e32 v56, v60, v56
	v_mov_b32_e32 v57, v56
	s_nop 1
	v_permlane16_swap_b32_e32 v56, v57
	global_store_dwordx4 v74, v[68:71], s[8:9]
	s_waitcnt lgkmcnt(0)
	v_add_f32_e32 v56, v56, v57
	v_mov_b32_e32 v57, v56
	s_nop 1
	v_permlane32_swap_b32_e32 v56, v57
	s_and_saveexec_b64 s[2:3], s[36:37]
	s_cbranch_execz .LBB0_599
	v_lshl_add_u64 v[58:59], s[10:11], 0, v[72:73]
	v_lshl_add_u64 v[58:59], s[0:1], 2, v[58:59]
	s_lshl_b32 s96, s49, 2
	v_lshl_add_u64 v[58:59], v[58:59], 0, s[96:97]
	s_waitcnt lgkmcnt(0)
	v_add_f32_e32 v56, v56, v57
	global_store_dword v[58:59], v56, off

; __device__ __forceinline__ unsigned cvt_pk_bf16(float lo, float hi) { unsigned r; asm volatile("v_cvt_pk_bf16_f32 %0, %1, %2" : "=v"(r) : "v"(lo), "v"(hi)); return r; }
; __device__ __forceinline__ float shx(float v, int lane, int mask) { return __builtin_bit_cast(float, __builtin_amdgcn_ds_bpermute((lane ^ mask) << 2, __builtin_bit_cast(int, v))); }
; __device__ __forceinline__ f32x4 bf_lo4(unsigned a, unsigned b) { return (f32x4){__uint_as_float(a << 16), __uint_as_float(a & 0xffff0000u), __uint_as_float(b << 16), __uint_as_float(b & 0xffff0000u)}; }
;     __device__ __forceinline__ void operator()(AccT& acc, const Unit& u, int wr, int wc, int fr, int fq, PG8_LAS unsigned char*) const {
;     ...
;                     const f32x4 v0 = acc[ai][bj][m][0] + bf_lo4(bb.x, bb.y), v1 = acc[ai][bj][m][1] + bf_lo4(bb.z, bb.w);
;                     u32x4 w; w.x = cvt_pk_bf16(v0.x, v0.y); w.y = cvt_pk_bf16(v0.z, v0.w); w.z = cvt_pk_bf16(v1.x, v1.y); w.w = cvt_pk_bf16(v1.z, v1.w);
;                     if (fout) { float* fo = (float*)((char*)fout + (size_t)(e + bj * HALF) * 4u); *(f32x4*)fo = v0; *(f32x4*)(fo + 4) = v1; }
;                     else {
;                         *(u32x4*)((char*)hb + ((e + bj * HALF) * 2u)) = w;
;                         float ss = ((v0.x * v0.x + v0.y * v0.y) + (v0.z * v0.z + v0.w * v0.w)) + ((v1.x * v1.x + v1.y * v1.y) + (v1.z * v1.z + v1.w * v1.w));
;                         ss += shx(ss, lane, 16); ss += shx(ss, lane, 32);
;                         if (fq == 0) ssq[(size_t)row * 32 + u.pn * 8 + bj * 4 + wc] = ss; } } }
.LBB0_602:
.LBB0_603:
	v_mul_f32_e32 v53, v53, v53
	v_mul_f32_e32 v49, v49, v49
	v_fmac_f32_e32 v53, v52, v52
	v_mul_f32_e32 v52, v55, v55
	v_fmac_f32_e32 v49, v48, v48
	v_mul_f32_e32 v48, v51, v51
	v_fmac_f32_e32 v52, v54, v54
	v_fmac_f32_e32 v48, v50, v50
	v_add_f32_e32 v52, v53, v52
	v_add_f32_e32 v48, v49, v48
	v_add_f32_e32 v48, v52, v48
	v_mov_b32_e32 v49, v48
	s_nop 1
	v_permlane16_swap_b32_e32 v48, v49
	v_or_b32_e32 v50, 0x100, v74
	global_store_dwordx4 v50, v[56:59], s[8:9]
	s_waitcnt lgkmcnt(0)
	v_add_f32_e32 v48, v48, v49
	v_mov_b32_e32 v49, v48
	s_nop 1
	v_permlane32_swap_b32_e32 v48, v49
	s_and_saveexec_b64 s[2:3], s[36:37]
	s_cbranch_execz .LBB0_605
	v_lshl_add_u64 v[50:51], s[10:11], 0, v[72:73]
	v_lshl_add_u64 v[50:51], s[0:1], 2, v[50:51]
	s_lshl_b32 s96, s49, 2
	v_lshl_add_u64 v[50:51], v[50:51], 0, s[96:97]
	s_waitcnt lgkmcnt(0)
	v_add_f32_e32 v48, v48, v49
	global_store_dword v[50:51], v48, off offset:16

; __device__ __forceinline__ unsigned cvt_pk_bf16(float lo, float hi) { unsigned r; asm volatile("v_cvt_pk_bf16_f32 %0, %1, %2" : "=v"(r) : "v"(lo), "v"(hi)); return r; }
; __device__ __forceinline__ float shx(float v, int lane, int mask) { return __builtin_bit_cast(float, __builtin_amdgcn_ds_bpermute((lane ^ mask) << 2, __builtin_bit_cast(int, v))); }
; __device__ __forceinline__ f32x4 bf_lo4(unsigned a, unsigned b) { return (f32x4){__uint_as_float(a << 16), __uint_as_float(a & 0xffff0000u), __uint_as_float(b << 16), __uint_as_float(b & 0xffff0000u)}; }
;     __device__ __forceinline__ void operator()(AccT& acc, const Unit& u, int wr, int wc, int fr, int fq, PG8_LAS unsigned char*) const {
;     ...
;                     const f32x4 v0 = acc[ai][bj][m][0] + bf_lo4(bb.x, bb.y), v1 = acc[ai][bj][m][1] + bf_lo4(bb.z, bb.w);
;                     u32x4 w; w.x = cvt_pk_bf16(v0.x, v0.y); w.y = cvt_pk_bf16(v0.z, v0.w); w.z = cvt_pk_bf16(v1.x, v1.y); w.w = cvt_pk_bf16(v1.z, v1.w);
;                     if (fout) { float* fo = (float*)((char*)fout + (size_t)(e + bj * HALF) * 4u); *(f32x4*)fo = v0; *(f32x4*)(fo + 4) = v1; }
;                     else {
;                         *(u32x4*)((char*)hb + ((e + bj * HALF) * 2u)) = w;
;                         float ss = ((v0.x * v0.x + v0.y * v0.y) + (v0.z * v0.z + v0.w * v0.w)) + ((v1.x * v1.x + v1.y * v1.y) + (v1.z * v1.z + v1.w * v1.w));
;                         ss += shx(ss, lane, 16); ss += shx(ss, lane, 32);
;                         if (fq == 0) ssq[(size_t)row * 32 + u.pn * 8 + bj * 4 + wc] = ss; } } }
.LBB0_609:
	v_ashrrev_i32_e32 v53, 31, v52
	v_lshlrev_b32_e32 v54, 1, v208
	s_andn2_b64 vcc, exec, s[2:3]
	v_lshlrev_b64 v[52:53], 7, v[52:53]
	s_cbranch_vccnz .LBB0_613
	v_mul_f32_e32 v45, v45, v45
	v_mul_f32_e32 v41, v41, v41
	v_fmac_f32_e32 v45, v44, v44
	v_mul_f32_e32 v44, v47, v47
	v_fmac_f32_e32 v41, v40, v40
	v_mul_f32_e32 v40, v43, v43
	v_fmac_f32_e32 v44, v46, v46
	v_fmac_f32_e32 v40, v42, v42
	v_add_f32_e32 v44, v45, v44
	v_add_f32_e32 v40, v41, v40
	v_add_f32_e32 v40, v44, v40
	v_mov_b32_e32 v41, v40
	s_nop 1
	v_permlane16_swap_b32_e32 v40, v41
	global_store_dwordx4 v54, v[48:51], s[8:9]
	s_waitcnt lgkmcnt(0)
	v_add_f32_e32 v40, v40, v41
	v_mov_b32_e32 v41, v40
	s_nop 1
	v_permlane32_swap_b32_e32 v40, v41
	s_and_saveexec_b64 s[2:3], s[36:37]
	s_cbranch_execz .LBB0_612
	v_lshl_add_u64 v[42:43], s[10:11], 0, v[52:53]
	v_lshl_add_u64 v[42:43], s[0:1], 2, v[42:43]
	s_lshl_b32 s96, s49, 2
	v_lshl_add_u64 v[42:43], v[42:43], 0, s[96:97]
	s_waitcnt lgkmcnt(0)
	v_add_f32_e32 v40, v40, v41
	global_store_dword v[42:43], v40, off

; __device__ __forceinline__ unsigned cvt_pk_bf16(float lo, float hi) { unsigned r; asm volatile("v_cvt_pk_bf16_f32 %0, %1, %2" : "=v"(r) : "v"(lo), "v"(hi)); return r; }
; __device__ __forceinline__ float shx(float v, int lane, int mask) { return __builtin_bit_cast(float, __builtin_amdgcn_ds_bpermute((lane ^ mask) << 2, __builtin_bit_cast(int, v))); }
; __device__ __forceinline__ f32x4 bf_lo4(unsigned a, unsigned b) { return (f32x4){__uint_as_float(a << 16), __uint_as_float(a & 0xffff0000u), __uint_as_float(b << 16), __uint_as_float(b & 0xffff0000u)}; }
;     __device__ __forceinline__ void operator()(AccT& acc, const Unit& u, int wr, int wc, int fr, int fq, PG8_LAS unsigned char*) const {
;     ...
;                     const f32x4 v0 = acc[ai][bj][m][0] + bf_lo4(bb.x, bb.y), v1 = acc[ai][bj][m][1] + bf_lo4(bb.z, bb.w);
;                     u32x4 w; w.x = cvt_pk_bf16(v0.x, v0.y); w.y = cvt_pk_bf16(v0.z, v0.w); w.z = cvt_pk_bf16(v1.x, v1.y); w.w = cvt_pk_bf16(v1.z, v1.w);
;                     if (fout) { float* fo = (float*)((char*)fout + (size_t)(e + bj * HALF) * 4u); *(f32x4*)fo = v0; *(f32x4*)(fo + 4) = v1; }
;                     else {
;                         *(u32x4*)((char*)hb + ((e + bj * HALF) * 2u)) = w;
;                         float ss = ((v0.x * v0.x + v0.y * v0.y) + (v0.z * v0.z + v0.w * v0.w)) + ((v1.x * v1.x + v1.y * v1.y) + (v1.z * v1.z + v1.w * v1.w));
;                         ss += shx(ss, lane, 16); ss += shx(ss, lane, 32);
;                         if (fq == 0) ssq[(size_t)row * 32 + u.pn * 8 + bj * 4 + wc] = ss; } } }
.LBB0_615:
.LBB0_616:
	v_mul_f32_e32 v37, v37, v37
	v_mul_f32_e32 v33, v33, v33
	v_fmac_f32_e32 v37, v36, v36
	v_mul_f32_e32 v36, v39, v39
	v_fmac_f32_e32 v33, v32, v32
	v_mul_f32_e32 v32, v35, v35
	v_fmac_f32_e32 v36, v38, v38
	v_fmac_f32_e32 v32, v34, v34
	v_add_f32_e32 v36, v37, v36
	v_add_f32_e32 v32, v33, v32
	v_add_f32_e32 v32, v36, v32
	v_mov_b32_e32 v33, v32
	s_nop 1
	v_permlane16_swap_b32_e32 v32, v33
	v_or_b32_e32 v34, 0x100, v54
	global_store_dwordx4 v34, v[40:43], s[8:9]
	s_waitcnt lgkmcnt(0)
	v_add_f32_e32 v32, v32, v33
	v_mov_b32_e32 v33, v32
	s_nop 1
	v_permlane32_swap_b32_e32 v32, v33
	s_and_saveexec_b64 s[2:3], s[36:37]
	s_cbranch_execz .LBB0_618
	v_lshl_add_u64 v[34:35], s[10:11], 0, v[52:53]
	v_lshl_add_u64 v[34:35], s[0:1], 2, v[34:35]
	s_lshl_b32 s96, s49, 2
	v_lshl_add_u64 v[34:35], v[34:35], 0, s[96:97]
	s_waitcnt lgkmcnt(0)
	v_add_f32_e32 v32, v32, v33
	global_store_dword v[34:35], v32, off offset:16

; __device__ __forceinline__ unsigned cvt_pk_bf16(float lo, float hi) { unsigned r; asm volatile("v_cvt_pk_bf16_f32 %0, %1, %2" : "=v"(r) : "v"(lo), "v"(hi)); return r; }
; __device__ __forceinline__ float shx(float v, int lane, int mask) { return __builtin_bit_cast(float, __builtin_amdgcn_ds_bpermute((lane ^ mask) << 2, __builtin_bit_cast(int, v))); }
; __device__ __forceinline__ f32x4 bf_lo4(unsigned a, unsigned b) { return (f32x4){__uint_as_float(a << 16), __uint_as_float(a & 0xffff0000u), __uint_as_float(b << 16), __uint_as_float(b & 0xffff0000u)}; }
;     __device__ __forceinline__ void operator()(AccT& acc, const Unit& u, int wr, int wc, int fr, int fq, PG8_LAS unsigned char*) const {
;     ...
;                     const f32x4 v0 = acc[ai][bj][m][0] + bf_lo4(bb.x, bb.y), v1 = acc[ai][bj][m][1] + bf_lo4(bb.z, bb.w);
;                     u32x4 w; w.x = cvt_pk_bf16(v0.x, v0.y); w.y = cvt_pk_bf16(v0.z, v0.w); w.z = cvt_pk_bf16(v1.x, v1.y); w.w = cvt_pk_bf16(v1.z, v1.w);
;                     if (fout) { float* fo = (float*)((char*)fout + (size_t)(e + bj * HALF) * 4u); *(f32x4*)fo = v0; *(f32x4*)(fo + 4) = v1; }
;                     else {
;                         *(u32x4*)((char*)hb + ((e + bj * HALF) * 2u)) = w;
;                         float ss = ((v0.x * v0.x + v0.y * v0.y) + (v0.z * v0.z + v0.w * v0.w)) + ((v1.x * v1.x + v1.y * v1.y) + (v1.z * v1.z + v1.w * v1.w));
;                         ss += shx(ss, lane, 16); ss += shx(ss, lane, 32);
;                         if (fq == 0) ssq[(size_t)row * 32 + u.pn * 8 + bj * 4 + wc] = ss; } } }
.LBB0_622:
	v_ashrrev_i32_e32 v37, 31, v36
	v_lshlrev_b32_e32 v38, 1, v208
	s_andn2_b64 vcc, exec, s[2:3]
	v_lshlrev_b64 v[36:37], 7, v[36:37]
	s_cbranch_vccnz .LBB0_626
	v_mul_f32_e32 v29, v29, v29
	v_mul_f32_e32 v25, v25, v25
	v_fmac_f32_e32 v29, v28, v28
	v_mul_f32_e32 v28, v31, v31
	v_fmac_f32_e32 v25, v24, v24
	v_mul_f32_e32 v24, v27, v27
	v_fmac_f32_e32 v28, v30, v30
	v_fmac_f32_e32 v24, v26, v26
	v_add_f32_e32 v28, v29, v28
	v_add_f32_e32 v24, v25, v24
	v_add_f32_e32 v24, v28, v24
	v_mov_b32_e32 v25, v24
	s_nop 1
	v_permlane16_swap_b32_e32 v24, v25
	global_store_dwordx4 v38, v[32:35], s[8:9]
	s_waitcnt lgkmcnt(0)
	v_add_f32_e32 v24, v24, v25
	v_mov_b32_e32 v25, v24
	s_nop 1
	v_permlane32_swap_b32_e32 v24, v25
	s_and_saveexec_b64 s[2:3], s[36:37]
	s_cbranch_execz .LBB0_625
	v_lshl_add_u64 v[26:27], s[10:11], 0, v[36:37]
	v_lshl_add_u64 v[26:27], s[0:1], 2, v[26:27]
	s_lshl_b32 s96, s49, 2
	v_lshl_add_u64 v[26:27], v[26:27], 0, s[96:97]
	s_waitcnt lgkmcnt(0)
	v_add_f32_e32 v24, v24, v25
	global_store_dword v[26:27], v24, off

; __device__ __forceinline__ unsigned cvt_pk_bf16(float lo, float hi) { unsigned r; asm volatile("v_cvt_pk_bf16_f32 %0, %1, %2" : "=v"(r) : "v"(lo), "v"(hi)); return r; }
; __device__ __forceinline__ float shx(float v, int lane, int mask) { return __builtin_bit_cast(float, __builtin_amdgcn_ds_bpermute((lane ^ mask) << 2, __builtin_bit_cast(int, v))); }
; __device__ __forceinline__ f32x4 bf_lo4(unsigned a, unsigned b) { return (f32x4){__uint_as_float(a << 16), __uint_as_float(a & 0xffff0000u), __uint_as_float(b << 16), __uint_as_float(b & 0xffff0000u)}; }
;     __device__ __forceinline__ void operator()(AccT& acc, const Unit& u, int wr, int wc, int fr, int fq, PG8_LAS unsigned char*) const {
;     ...
;                     const f32x4 v0 = acc[ai][bj][m][0] + bf_lo4(bb.x, bb.y), v1 = acc[ai][bj][m][1] + bf_lo4(bb.z, bb.w);
;                     u32x4 w; w.x = cvt_pk_bf16(v0.x, v0.y); w.y = cvt_pk_bf16(v0.z, v0.w); w.z = cvt_pk_bf16(v1.x, v1.y); w.w = cvt_pk_bf16(v1.z, v1.w);
;                     if (fout) { float* fo = (float*)((char*)fout + (size_t)(e + bj * HALF) * 4u); *(f32x4*)fo = v0; *(f32x4*)(fo + 4) = v1; }
;                     else {
;                         *(u32x4*)((char*)hb + ((e + bj * HALF) * 2u)) = w;
;                         float ss = ((v0.x * v0.x + v0.y * v0.y) + (v0.z * v0.z + v0.w * v0.w)) + ((v1.x * v1.x + v1.y * v1.y) + (v1.z * v1.z + v1.w * v1.w));
;                         ss += shx(ss, lane, 16); ss += shx(ss, lane, 32);
;                         if (fq == 0) ssq[(size_t)row * 32 + u.pn * 8 + bj * 4 + wc] = ss; } } }
.LBB0_628:
.LBB0_629:
	v_mul_f32_e32 v21, v21, v21
	v_mul_f32_e32 v17, v17, v17
	v_fmac_f32_e32 v21, v20, v20
	v_mul_f32_e32 v20, v23, v23
	v_fmac_f32_e32 v17, v16, v16
	v_mul_f32_e32 v16, v19, v19
	v_fmac_f32_e32 v20, v22, v22
	v_fmac_f32_e32 v16, v18, v18
	v_add_f32_e32 v20, v21, v20
	v_add_f32_e32 v16, v17, v16
	v_add_f32_e32 v16, v20, v16
	v_mov_b32_e32 v17, v16
	s_nop 1
	v_permlane16_swap_b32_e32 v16, v17
	v_or_b32_e32 v18, 0x100, v38
	global_store_dwordx4 v18, v[24:27], s[8:9]
	s_waitcnt lgkmcnt(0)
	v_add_f32_e32 v16, v16, v17
	v_mov_b32_e32 v17, v16
	s_nop 1
	v_permlane32_swap_b32_e32 v16, v17
	s_and_saveexec_b64 s[2:3], s[36:37]
	s_cbranch_execz .LBB0_631
	v_lshl_add_u64 v[18:19], s[10:11], 0, v[36:37]
	v_lshl_add_u64 v[18:19], s[0:1], 2, v[18:19]
	s_lshl_b32 s96, s49, 2
	v_lshl_add_u64 v[18:19], v[18:19], 0, s[96:97]
	s_waitcnt lgkmcnt(0)
	v_add_f32_e32 v16, v16, v17
	global_store_dword v[18:19], v16, off offset:16

; __device__ __forceinline__ unsigned cvt_pk_bf16(float lo, float hi) { unsigned r; asm volatile("v_cvt_pk_bf16_f32 %0, %1, %2" : "=v"(r) : "v"(lo), "v"(hi)); return r; }
; __device__ __forceinline__ float shx(float v, int lane, int mask) { return __builtin_bit_cast(float, __builtin_amdgcn_ds_bpermute((lane ^ mask) << 2, __builtin_bit_cast(int, v))); }
; __device__ __forceinline__ f32x4 bf_lo4(unsigned a, unsigned b) { return (f32x4){__uint_as_float(a << 16), __uint_as_float(a & 0xffff0000u), __uint_as_float(b << 16), __uint_as_float(b & 0xffff0000u)}; }
;     __device__ __forceinline__ void operator()(AccT& acc, const Unit& u, int wr, int wc, int fr, int fq, PG8_LAS unsigned char*) const {
;     ...
;                     const f32x4 v0 = acc[ai][bj][m][0] + bf_lo4(bb.x, bb.y), v1 = acc[ai][bj][m][1] + bf_lo4(bb.z, bb.w);
;                     u32x4 w; w.x = cvt_pk_bf16(v0.x, v0.y); w.y = cvt_pk_bf16(v0.z, v0.w); w.z = cvt_pk_bf16(v1.x, v1.y); w.w = cvt_pk_bf16(v1.z, v1.w);
;                     if (fout) { float* fo = (float*)((char*)fout + (size_t)(e + bj * HALF) * 4u); *(f32x4*)fo = v0; *(f32x4*)(fo + 4) = v1; }
;                     else {
;                         *(u32x4*)((char*)hb + ((e + bj * HALF) * 2u)) = w;
;                         float ss = ((v0.x * v0.x + v0.y * v0.y) + (v0.z * v0.z + v0.w * v0.w)) + ((v1.x * v1.x + v1.y * v1.y) + (v1.z * v1.z + v1.w * v1.w));
;                         ss += shx(ss, lane, 16); ss += shx(ss, lane, 32);
;                         if (fq == 0) ssq[(size_t)row * 32 + u.pn * 8 + bj * 4 + wc] = ss; } } }
.LBB0_635:
	v_ashrrev_i32_e32 v21, 31, v20
	v_lshlrev_b32_e32 v22, 1, v208
	s_andn2_b64 vcc, exec, s[2:3]
	v_lshlrev_b64 v[20:21], 7, v[20:21]
	s_cbranch_vccnz .LBB0_639
	v_mul_f32_e32 v13, v13, v13
	v_mul_f32_e32 v9, v9, v9
	v_fmac_f32_e32 v13, v12, v12
	v_mul_f32_e32 v12, v15, v15
	v_fmac_f32_e32 v9, v8, v8
	v_mul_f32_e32 v8, v11, v11
	v_fmac_f32_e32 v12, v14, v14
	v_fmac_f32_e32 v8, v10, v10
	v_add_f32_e32 v12, v13, v12
	v_add_f32_e32 v8, v9, v8
	v_add_f32_e32 v8, v12, v8
	v_mov_b32_e32 v9, v8
	s_nop 1
	v_permlane16_swap_b32_e32 v8, v9
	global_store_dwordx4 v22, v[16:19], s[8:9]
	s_waitcnt lgkmcnt(0)
	v_add_f32_e32 v8, v8, v9
	v_mov_b32_e32 v9, v8
	s_nop 1
	v_permlane32_swap_b32_e32 v8, v9
	s_and_saveexec_b64 s[2:3], s[36:37]
	s_cbranch_execz .LBB0_638
	v_lshl_add_u64 v[10:11], s[10:11], 0, v[20:21]
	v_lshl_add_u64 v[10:11], s[0:1], 2, v[10:11]
	s_lshl_b32 s96, s49, 2
	v_lshl_add_u64 v[10:11], v[10:11], 0, s[96:97]
	s_waitcnt lgkmcnt(0)
	v_add_f32_e32 v8, v8, v9
	global_store_dword v[10:11], v8, off

; __device__ __forceinline__ unsigned cvt_pk_bf16(float lo, float hi) { unsigned r; asm volatile("v_cvt_pk_bf16_f32 %0, %1, %2" : "=v"(r) : "v"(lo), "v"(hi)); return r; }
; __device__ __forceinline__ float shx(float v, int lane, int mask) { return __builtin_bit_cast(float, __builtin_amdgcn_ds_bpermute((lane ^ mask) << 2, __builtin_bit_cast(int, v))); }
; __device__ __forceinline__ f32x4 bf_lo4(unsigned a, unsigned b) { return (f32x4){__uint_as_float(a << 16), __uint_as_float(a & 0xffff0000u), __uint_as_float(b << 16), __uint_as_float(b & 0xffff0000u)}; }
;     __device__ __forceinline__ void operator()(AccT& acc, const Unit& u, int wr, int wc, int fr, int fq, PG8_LAS unsigned char*) const {
;     ...
;                     const f32x4 v0 = acc[ai][bj][m][0] + bf_lo4(bb.x, bb.y), v1 = acc[ai][bj][m][1] + bf_lo4(bb.z, bb.w);
;                     u32x4 w; w.x = cvt_pk_bf16(v0.x, v0.y); w.y = cvt_pk_bf16(v0.z, v0.w); w.z = cvt_pk_bf16(v1.x, v1.y); w.w = cvt_pk_bf16(v1.z, v1.w);
;                     if (fout) { float* fo = (float*)((char*)fout + (size_t)(e + bj * HALF) * 4u); *(f32x4*)fo = v0; *(f32x4*)(fo + 4) = v1; }
;                     else {
;                         *(u32x4*)((char*)hb + ((e + bj * HALF) * 2u)) = w;
;                         float ss = ((v0.x * v0.x + v0.y * v0.y) + (v0.z * v0.z + v0.w * v0.w)) + ((v1.x * v1.x + v1.y * v1.y) + (v1.z * v1.z + v1.w * v1.w));
;                         ss += shx(ss, lane, 16); ss += shx(ss, lane, 32);
;                         if (fq == 0) ssq[(size_t)row * 32 + u.pn * 8 + bj * 4 + wc] = ss; } } }
.LBB0_641:
.LBB0_642:
	v_mul_f32_e32 v5, v5, v5
	v_mul_f32_e32 v1, v1, v1
	v_fmac_f32_e32 v5, v4, v4
	v_mul_f32_e32 v4, v7, v7
	v_fmac_f32_e32 v1, v0, v0
	v_mul_f32_e32 v0, v3, v3
	v_fmac_f32_e32 v4, v6, v6
	v_fmac_f32_e32 v0, v2, v2
	v_add_f32_e32 v4, v5, v4
	v_add_f32_e32 v0, v1, v0
	v_add_f32_e32 v0, v4, v0
	v_mov_b32_e32 v1, v0
	s_nop 1
	v_permlane16_swap_b32_e32 v0, v1
	v_or_b32_e32 v2, 0x100, v22
	global_store_dwordx4 v2, v[8:11], s[8:9]
	s_waitcnt lgkmcnt(0)
	v_add_f32_e32 v0, v0, v1
	v_mov_b32_e32 v1, v0
	s_nop 1
	v_permlane32_swap_b32_e32 v0, v1
	s_and_saveexec_b64 s[2:3], s[36:37]
	s_cbranch_execz .LBB0_644
	v_lshl_add_u64 v[2:3], s[10:11], 0, v[20:21]
	v_lshl_add_u64 v[2:3], s[0:1], 2, v[2:3]
	s_lshl_b32 s96, s49, 2
	v_lshl_add_u64 v[2:3], v[2:3], 0, s[96:97]
	s_waitcnt lgkmcnt(0)
	v_add_f32_e32 v0, v0, v1
	global_store_dword v[2:3], v0, off offset:16

; __device__ __forceinline__ float shx(float v, int lane, int mask) { return __builtin_bit_cast(float, __builtin_amdgcn_ds_bpermute((lane ^ mask) << 2, __builtin_bit_cast(int, v))); }
;     __device__ __forceinline__ void operator()(AccT& acc, const Unit& u, int wr, int wc, int fr, int fq, PG8_LAS unsigned char* lds) const {
;     ...
;                 for (int m = 0; m < 4; ++m) { float s[2];
; #pragma unroll
;                     for (int bj = 0; bj < 2; ++bj) { const f32x4 a = acc[ai][bj][m][0], b = acc[ai][bj][m][1];
;                         s[bj] = ((a.x * a.x + a.y * a.y) + (a.z * a.z + a.w * a.w)) + ((b.x * b.x + b.y * b.y) + (b.z * b.z + b.w * b.w)); }
;                     if (NSEG == 1) { s[0] += s[1]; s[1] = 0.f; }
; #pragma unroll
;                     for (int sg = 0; sg < NSEG; ++sg) { float t = s[sg]; t += shx(t, fr + 16 * fq, 16); t += shx(t, fr + 16 * fq, 32);
;                         if (fq == 0) P[((ai * HALF + wr * 64 + m * 16 + fr) * 2 + sg) * 4 + wc] = t; } }
.LBB0_732:
	ds_read2_b32 v[162:163], v191 offset1:16
	ds_read2_b32 v[160:161], v191 offset0:32 offset1:48
	ds_read2_b32 v[158:159], v191 offset0:128 offset1:144
	ds_read2_b32 v[156:157], v191 offset0:160 offset1:176
	s_and_b64 vcc, exec, s[42:43]
	s_cbranch_vccnz .LBB0_766
	v_mul_f32_e32 v164, v125, v125
	v_mul_f32_e32 v165, v127, v127
	v_fmac_f32_e32 v164, v124, v124
	v_fmac_f32_e32 v165, v126, v126
	v_add_f32_e32 v164, v164, v165
	v_mul_f32_e32 v165, v121, v121
	v_mul_f32_e32 v166, v123, v123
	v_fmac_f32_e32 v165, v120, v120
	v_fmac_f32_e32 v166, v122, v122
	v_add_f32_e32 v165, v165, v166
	v_add_f32_e32 v164, v164, v165
	v_mov_b32_e32 v165, v164
	s_nop 1
	v_permlane16_swap_b32_e32 v164, v165
	s_waitcnt lgkmcnt(0)
	v_add_f32_e32 v165, v164, v165
	v_mov_b32_e32 v166, v165
	s_nop 1
	v_permlane32_swap_b32_e32 v165, v166
	v_add_u32_e32 v164, s55, v188
	s_and_saveexec_b64 s[0:1], s[36:37]
	s_cbranch_execz .LBB0_735
	s_waitcnt lgkmcnt(0)
	v_add_f32_e32 v165, v165, v166
	ds_write_b32 v164, v165
.LBB0_735:
	s_or_b64 exec, exec, s[0:1]
	v_mul_f32_e32 v165, v117, v117
	s_waitcnt lgkmcnt(0)
	v_mul_f32_e32 v166, v119, v119
	v_fmac_f32_e32 v165, v116, v116
	v_fmac_f32_e32 v166, v118, v118
	v_add_f32_e32 v165, v165, v166
	v_mul_f32_e32 v166, v109, v109
	v_mul_f32_e32 v167, v111, v111
	v_fmac_f32_e32 v166, v108, v108
	v_fmac_f32_e32 v167, v110, v110
	v_add_f32_e32 v166, v166, v167
	v_add_f32_e32 v165, v165, v166
	v_mov_b32_e32 v166, v165
	s_nop 1
	v_permlane16_swap_b32_e32 v165, v166
	s_waitcnt lgkmcnt(0)
	v_add_f32_e32 v165, v165, v166
	v_mov_b32_e32 v166, v165
	s_nop 1
	v_permlane32_swap_b32_e32 v165, v166
	s_and_saveexec_b64 s[0:1], s[36:37]
	s_cbranch_execz .LBB0_737
	s_waitcnt lgkmcnt(0)
	v_add_f32_e32 v165, v165, v166
	ds_write_b32 v164, v165 offset:16
.LBB0_737:
	s_or_b64 exec, exec, s[0:1]
	v_mul_f32_e32 v165, v113, v113
	s_waitcnt lgkmcnt(0)
	v_mul_f32_e32 v166, v115, v115
	v_fmac_f32_e32 v165, v112, v112
	v_fmac_f32_e32 v166, v114, v114
	v_add_f32_e32 v165, v165, v166
	v_mul_f32_e32 v166, v105, v105
	v_mul_f32_e32 v167, v107, v107
	v_fmac_f32_e32 v166, v104, v104
	v_fmac_f32_e32 v167, v106, v106
	v_add_f32_e32 v166, v166, v167
	v_add_f32_e32 v165, v165, v166
	v_mov_b32_e32 v166, v165
	s_nop 1
	v_permlane16_swap_b32_e32 v165, v166
	s_waitcnt lgkmcnt(0)
	v_add_f32_e32 v165, v165, v166
	v_mov_b32_e32 v166, v165
	s_nop 1
	v_permlane32_swap_b32_e32 v165, v166
	s_and_saveexec_b64 s[0:1], s[36:37]
	s_cbranch_execz .LBB0_739
	s_waitcnt lgkmcnt(0)
	v_add_f32_e32 v165, v165, v166
	ds_write_b32 v164, v165 offset:512
.LBB0_739:
	s_or_b64 exec, exec, s[0:1]
	v_mul_f32_e32 v165, v101, v101
	s_waitcnt lgkmcnt(0)
	v_mul_f32_e32 v166, v103, v103
	v_fmac_f32_e32 v165, v100, v100
	v_fmac_f32_e32 v166, v102, v102
	v_add_f32_e32 v165, v165, v166
	v_mul_f32_e32 v166, v93, v93
	v_mul_f32_e32 v167, v95, v95
	v_fmac_f32_e32 v166, v92, v92
	v_fmac_f32_e32 v167, v94, v94
	v_add_f32_e32 v166, v166, v167
	v_add_f32_e32 v165, v165, v166
	v_mov_b32_e32 v166, v165
	s_nop 1
	v_permlane16_swap_b32_e32 v165, v166
	s_waitcnt lgkmcnt(0)
	v_add_f32_e32 v165, v165, v166
	v_mov_b32_e32 v166, v165
	s_nop 1
	v_permlane32_swap_b32_e32 v165, v166
	s_and_saveexec_b64 s[0:1], s[36:37]
	s_cbranch_execz .LBB0_741
	s_waitcnt lgkmcnt(0)
	v_add_f32_e32 v165, v165, v166
	ds_write_b32 v164, v165 offset:528
.LBB0_741:
	s_or_b64 exec, exec, s[0:1]
	v_mul_f32_e32 v165, v97, v97
	s_waitcnt lgkmcnt(0)
	v_mul_f32_e32 v166, v99, v99
	v_fmac_f32_e32 v165, v96, v96
	v_fmac_f32_e32 v166, v98, v98
	v_add_f32_e32 v165, v165, v166
	v_mul_f32_e32 v166, v89, v89
	v_mul_f32_e32 v167, v91, v91
	v_fmac_f32_e32 v166, v88, v88
	v_fmac_f32_e32 v167, v90, v90
	v_add_f32_e32 v166, v166, v167
	v_add_f32_e32 v165, v165, v166
	v_mov_b32_e32 v166, v165
	s_nop 1
	v_permlane16_swap_b32_e32 v165, v166
	s_waitcnt lgkmcnt(0)
	v_add_f32_e32 v165, v165, v166
	v_mov_b32_e32 v166, v165
	s_nop 1
	v_permlane32_swap_b32_e32 v165, v166
	s_and_saveexec_b64 s[0:1], s[36:37]
	s_cbranch_execz .LBB0_743
	s_waitcnt lgkmcnt(0)
	v_add_f32_e32 v165, v165, v166
	ds_write_b32 v164, v165 offset:1024
.LBB0_743:
	s_or_b64 exec, exec, s[0:1]
	v_mul_f32_e32 v165, v85, v85
	s_waitcnt lgkmcnt(0)
	v_mul_f32_e32 v166, v87, v87
	v_fmac_f32_e32 v165, v84, v84
	v_fmac_f32_e32 v166, v86, v86
	v_add_f32_e32 v165, v165, v166
	v_mul_f32_e32 v166, v77, v77
	v_mul_f32_e32 v167, v79, v79
	v_fmac_f32_e32 v166, v76, v76
	v_fmac_f32_e32 v167, v78, v78
	v_add_f32_e32 v166, v166, v167
	v_add_f32_e32 v165, v165, v166
	v_mov_b32_e32 v166, v165
	s_nop 1
	v_permlane16_swap_b32_e32 v165, v166
	s_waitcnt lgkmcnt(0)
	v_add_f32_e32 v165, v165, v166
	v_mov_b32_e32 v166, v165
	s_nop 1
	v_permlane32_swap_b32_e32 v165, v166
	s_and_saveexec_b64 s[0:1], s[36:37]
	s_cbranch_execz .LBB0_745
	s_waitcnt lgkmcnt(0)
	v_add_f32_e32 v165, v165, v166
	ds_write_b32 v164, v165 offset:1040
.LBB0_745:
	s_or_b64 exec, exec, s[0:1]
	v_mul_f32_e32 v165, v81, v81
	s_waitcnt lgkmcnt(0)
	v_mul_f32_e32 v166, v83, v83
	v_fmac_f32_e32 v165, v80, v80
	v_fmac_f32_e32 v166, v82, v82
	v_add_f32_e32 v165, v165, v166
	v_mul_f32_e32 v166, v73, v73
	v_mul_f32_e32 v167, v75, v75
	v_fmac_f32_e32 v166, v72, v72
	v_fmac_f32_e32 v167, v74, v74
	v_add_f32_e32 v166, v166, v167
	v_add_f32_e32 v165, v165, v166
	v_mov_b32_e32 v166, v165
	s_nop 1
	v_permlane16_swap_b32_e32 v165, v166
	s_waitcnt lgkmcnt(0)
	v_add_f32_e32 v165, v165, v166
	v_mov_b32_e32 v166, v165
	s_nop 1
	v_permlane32_swap_b32_e32 v165, v166
	s_and_saveexec_b64 s[0:1], s[36:37]
	s_cbranch_execz .LBB0_747
	s_waitcnt lgkmcnt(0)
	v_add_f32_e32 v165, v165, v166
	ds_write_b32 v164, v165 offset:1536
; __device__ __forceinline__ float shx(float v, int lane, int mask) { return __builtin_bit_cast(float, __builtin_amdgcn_ds_bpermute((lane ^ mask) << 2, __builtin_bit_cast(int, v))); }
;     __device__ __forceinline__ void operator()(AccT& acc, const Unit& u, int wr, int wc, int fr, int fq, PG8_LAS unsigned char* lds) const {
;     ...
;                 for (int m = 0; m < 4; ++m) { float s[2];
; #pragma unroll
;                     for (int bj = 0; bj < 2; ++bj) { const f32x4 a = acc[ai][bj][m][0], b = acc[ai][bj][m][1];
;                         s[bj] = ((a.x * a.x + a.y * a.y) + (a.z * a.z + a.w * a.w)) + ((b.x * b.x + b.y * b.y) + (b.z * b.z + b.w * b.w)); }
;                     if (NSEG == 1) { s[0] += s[1]; s[1] = 0.f; }
; #pragma unroll
;                     for (int sg = 0; sg < NSEG; ++sg) { float t = s[sg]; t += shx(t, fr + 16 * fq, 16); t += shx(t, fr + 16 * fq, 32);
;                         if (fq == 0) P[((ai * HALF + wr * 64 + m * 16 + fr) * 2 + sg) * 4 + wc] = t; } }
.LBB0_747:
	s_or_b64 exec, exec, s[0:1]
	v_mul_f32_e32 v165, v69, v69
	s_waitcnt lgkmcnt(0)
	v_mul_f32_e32 v166, v71, v71
	v_fmac_f32_e32 v165, v68, v68
	v_fmac_f32_e32 v166, v70, v70
	v_add_f32_e32 v165, v165, v166
	v_mul_f32_e32 v166, v65, v65
	v_mul_f32_e32 v167, v67, v67
	v_fmac_f32_e32 v166, v64, v64
	v_fmac_f32_e32 v167, v66, v66
	v_add_f32_e32 v166, v166, v167
	v_add_f32_e32 v165, v165, v166
	v_mov_b32_e32 v166, v165
	s_nop 1
	v_permlane16_swap_b32_e32 v165, v166
	s_waitcnt lgkmcnt(0)
	v_add_f32_e32 v165, v165, v166
	v_mov_b32_e32 v166, v165
	s_nop 1
	v_permlane32_swap_b32_e32 v165, v166
	s_and_saveexec_b64 s[0:1], s[36:37]
	s_cbranch_execz .LBB0_749
	s_waitcnt lgkmcnt(0)
	v_add_f32_e32 v165, v165, v166
	ds_write_b32 v164, v165 offset:1552
.LBB0_749:
	s_or_b64 exec, exec, s[0:1]
	v_mul_f32_e32 v165, v61, v61
	s_waitcnt lgkmcnt(0)
	v_mul_f32_e32 v166, v63, v63
	v_fmac_f32_e32 v165, v60, v60
	v_fmac_f32_e32 v166, v62, v62
	v_add_f32_e32 v165, v165, v166
	v_mul_f32_e32 v166, v57, v57
	v_mul_f32_e32 v167, v59, v59
	v_fmac_f32_e32 v166, v56, v56
	v_fmac_f32_e32 v167, v58, v58
	v_add_f32_e32 v166, v166, v167
	v_add_f32_e32 v165, v165, v166
	v_mov_b32_e32 v166, v165
	s_nop 1
	v_permlane16_swap_b32_e32 v165, v166
	s_waitcnt lgkmcnt(0)
	v_add_f32_e32 v165, v165, v166
	v_mov_b32_e32 v166, v165
	s_nop 1
	v_permlane32_swap_b32_e32 v165, v166
	s_and_saveexec_b64 s[0:1], s[36:37]
	s_cbranch_execz .LBB0_751
	s_waitcnt lgkmcnt(0)
	v_add_f32_e32 v165, v165, v166
	ds_write_b32 v164, v165 offset:4096
.LBB0_751:
	s_or_b64 exec, exec, s[0:1]
	v_mul_f32_e32 v165, v53, v53
	s_waitcnt lgkmcnt(0)
	v_mul_f32_e32 v166, v55, v55
	v_fmac_f32_e32 v165, v52, v52
	v_fmac_f32_e32 v166, v54, v54
	v_add_f32_e32 v165, v165, v166
	v_mul_f32_e32 v166, v45, v45
	v_mul_f32_e32 v167, v47, v47
	v_fmac_f32_e32 v166, v44, v44
	v_fmac_f32_e32 v167, v46, v46
	v_add_f32_e32 v166, v166, v167
	v_add_f32_e32 v165, v165, v166
	v_mov_b32_e32 v166, v165
	s_nop 1
	v_permlane16_swap_b32_e32 v165, v166
	s_waitcnt lgkmcnt(0)
	v_add_f32_e32 v165, v165, v166
	v_mov_b32_e32 v166, v165
	s_nop 1
	v_permlane32_swap_b32_e32 v165, v166
	s_and_saveexec_b64 s[0:1], s[36:37]
	s_cbranch_execz .LBB0_753
	s_waitcnt lgkmcnt(0)
	v_add_f32_e32 v165, v165, v166
	ds_write_b32 v164, v165 offset:4112
.LBB0_753:
	s_or_b64 exec, exec, s[0:1]
	v_mul_f32_e32 v165, v49, v49
	s_waitcnt lgkmcnt(0)
	v_mul_f32_e32 v166, v51, v51
	v_fmac_f32_e32 v165, v48, v48
	v_fmac_f32_e32 v166, v50, v50
	v_add_f32_e32 v165, v165, v166
	v_mul_f32_e32 v166, v41, v41
	v_mul_f32_e32 v167, v43, v43
	v_fmac_f32_e32 v166, v40, v40
	v_fmac_f32_e32 v167, v42, v42
	v_add_f32_e32 v166, v166, v167
	v_add_f32_e32 v165, v165, v166
	v_mov_b32_e32 v166, v165
	s_nop 1
	v_permlane16_swap_b32_e32 v165, v166
	s_waitcnt lgkmcnt(0)
	v_add_f32_e32 v165, v165, v166
	v_mov_b32_e32 v166, v165
	s_nop 1
	v_permlane32_swap_b32_e32 v165, v166
	s_and_saveexec_b64 s[0:1], s[36:37]
	s_cbranch_execz .LBB0_755
	s_waitcnt lgkmcnt(0)
	v_add_f32_e32 v165, v165, v166
	ds_write_b32 v164, v165 offset:4608
.LBB0_755:
	s_or_b64 exec, exec, s[0:1]
	v_mul_f32_e32 v165, v37, v37
	s_waitcnt lgkmcnt(0)
	v_mul_f32_e32 v166, v39, v39
	v_fmac_f32_e32 v165, v36, v36
	v_fmac_f32_e32 v166, v38, v38
	v_add_f32_e32 v165, v165, v166
	v_mul_f32_e32 v166, v29, v29
	v_mul_f32_e32 v167, v31, v31
	v_fmac_f32_e32 v166, v28, v28
	v_fmac_f32_e32 v167, v30, v30
	v_add_f32_e32 v166, v166, v167
	v_add_f32_e32 v165, v165, v166
	v_mov_b32_e32 v166, v165
	s_nop 1
	v_permlane16_swap_b32_e32 v165, v166
	s_waitcnt lgkmcnt(0)
	v_add_f32_e32 v165, v165, v166
	v_mov_b32_e32 v166, v165
	s_nop 1
	v_permlane32_swap_b32_e32 v165, v166
	s_and_saveexec_b64 s[0:1], s[36:37]
	s_cbranch_execz .LBB0_757
	s_waitcnt lgkmcnt(0)
	v_add_f32_e32 v165, v165, v166
	ds_write_b32 v164, v165 offset:4624
.LBB0_757:
	s_or_b64 exec, exec, s[0:1]
	v_mul_f32_e32 v165, v33, v33
	s_waitcnt lgkmcnt(0)
	v_mul_f32_e32 v166, v35, v35
	v_fmac_f32_e32 v165, v32, v32
	v_fmac_f32_e32 v166, v34, v34
	v_add_f32_e32 v165, v165, v166
	v_mul_f32_e32 v166, v25, v25
	v_mul_f32_e32 v167, v27, v27
	v_fmac_f32_e32 v166, v24, v24
	v_fmac_f32_e32 v167, v26, v26
	v_add_f32_e32 v166, v166, v167
	v_add_f32_e32 v165, v165, v166
	v_mov_b32_e32 v166, v165
	s_nop 1
	v_permlane16_swap_b32_e32 v165, v166
	s_waitcnt lgkmcnt(0)
	v_add_f32_e32 v165, v165, v166
	v_mov_b32_e32 v166, v165
	s_nop 1
	v_permlane32_swap_b32_e32 v165, v166
	s_and_saveexec_b64 s[0:1], s[36:37]
	s_cbranch_execz .LBB0_759
	s_waitcnt lgkmcnt(0)
	v_add_f32_e32 v165, v165, v166
	ds_write_b32 v164, v165 offset:5120
.LBB0_759:
	s_or_b64 exec, exec, s[0:1]
	v_mul_f32_e32 v165, v21, v21
	s_waitcnt lgkmcnt(0)
	v_mul_f32_e32 v166, v23, v23
	v_fmac_f32_e32 v165, v20, v20
	v_fmac_f32_e32 v166, v22, v22
	v_add_f32_e32 v165, v165, v166
	v_mul_f32_e32 v166, v13, v13
	v_mul_f32_e32 v167, v15, v15
	v_fmac_f32_e32 v166, v12, v12
	v_fmac_f32_e32 v167, v14, v14
	v_add_f32_e32 v166, v166, v167
	v_add_f32_e32 v165, v165, v166
	v_mov_b32_e32 v166, v165
	s_nop 1
	v_permlane16_swap_b32_e32 v165, v166
	s_waitcnt lgkmcnt(0)
	v_add_f32_e32 v165, v165, v166
	v_mov_b32_e32 v166, v165
	s_nop 1
	v_permlane32_swap_b32_e32 v165, v166
	s_and_saveexec_b64 s[0:1], s[36:37]
	s_cbranch_execz .LBB0_761
	s_waitcnt lgkmcnt(0)
	v_add_f32_e32 v165, v165, v166
	ds_write_b32 v164, v165 offset:5136
.LBB0_761:
	s_or_b64 exec, exec, s[0:1]
	v_mul_f32_e32 v165, v17, v17
	s_waitcnt lgkmcnt(0)
	v_mul_f32_e32 v166, v19, v19
	v_fmac_f32_e32 v165, v16, v16
	v_fmac_f32_e32 v166, v18, v18
	v_add_f32_e32 v165, v165, v166
	v_mul_f32_e32 v166, v9, v9
	v_mul_f32_e32 v167, v11, v11
	v_fmac_f32_e32 v166, v8, v8
	v_fmac_f32_e32 v167, v10, v10
	v_add_f32_e32 v166, v166, v167
	v_add_f32_e32 v165, v165, v166
	v_mov_b32_e32 v166, v165
	s_nop 1
	v_permlane16_swap_b32_e32 v165, v166
	s_waitcnt lgkmcnt(0)
	v_add_f32_e32 v165, v165, v166
	v_mov_b32_e32 v166, v165
	s_nop 1
	v_permlane32_swap_b32_e32 v165, v166
	s_and_saveexec_b64 s[0:1], s[36:37]
	s_cbranch_execz .LBB0_763
	s_waitcnt lgkmcnt(0)
	v_add_f32_e32 v165, v165, v166
	ds_write_b32 v164, v165 offset:5632
.LBB0_763:
	s_or_b64 exec, exec, s[0:1]
	v_mul_f32_e32 v165, v5, v5
	s_waitcnt lgkmcnt(0)
	v_mul_f32_e32 v166, v7, v7
	v_fmac_f32_e32 v165, v4, v4
	v_fmac_f32_e32 v166, v6, v6
	v_add_f32_e32 v165, v165, v166
	v_mul_f32_e32 v166, v1, v1
	v_mul_f32_e32 v167, v3, v3
	v_fmac_f32_e32 v166, v0, v0
	v_fmac_f32_e32 v167, v2, v2
	v_add_f32_e32 v166, v166, v167
	v_add_f32_e32 v165, v165, v166
	v_mov_b32_e32 v166, v165
	s_nop 1
	v_permlane16_swap_b32_e32 v165, v166
	s_waitcnt lgkmcnt(0)
	v_add_f32_e32 v165, v165, v166
	v_mov_b32_e32 v166, v165
	s_nop 1
	v_permlane32_swap_b32_e32 v165, v166
	s_and_saveexec_b64 s[0:1], s[36:37]
	s_cbranch_execz .LBB0_765
	s_waitcnt lgkmcnt(0)
	v_add_f32_e32 v165, v165, v166
	ds_write_b32 v164, v165 offset:5648
